# norm phases: lanes own 8 consecutive columns per slot pair so XN stores are 2 dwordx4 per row instead of 4 dwordx2 (half the store instructions), vmcnt waits recounted; on top of v23
# baseline (speedup 1.0000x reference)
; __device__ __forceinline__ void norm_mod_phase(const float* x, const float* x0src, size_t x0stride, float* h0buf, const float* g, const float* sh, const float* sc, bf16* XN, int gw, int NGW, int lane) {
;     const int wpb = NGW / BATCH, rpw = T / wpb;
;     const int b = gw / wpb, wi = gw - b * wpb;
;     f32x4 gm[4], s0[4];
; #pragma unroll
;     for (int j = 0; j < 4; ++j) { const int col = 4 * lane + 256 * j; gm[j] = *(const f32x4*)(g + col) * (*(const f32x4*)(sc + b * NMOD + col) + 1.f); s0[j] = *(const f32x4*)(sh + b * NMOD + col); }
.LBB0_161:
	s_abs_i32 s18, s19
	v_cvt_f32_u32_e32 v1, s18
	v_readlane_b32 s5, v255, 2
	s_ashr_i32 s20, s19, 31
	v_rcp_iflag_f32_e32 v1, v1
	v_mov_b32_e32 v2, s5
	s_sub_i32 s5, 0, s18
	ds_read_b64 v[2:3], v2
	v_mul_f32_e32 v1, 0x4f7ffffe, v1
	v_cvt_u32_f32_e32 v1, v1
	s_waitcnt lgkmcnt(0)
	v_readfirstlane_b32 s64, v2
	v_readfirstlane_b32 s65, v1
	s_mul_i32 s5, s5, s65
	s_mul_hi_u32 s5, s65, s5
	s_add_i32 s65, s65, s5
	s_lshr_b32 s5, s65, 20
	s_mul_i32 s8, s5, s18
	s_sub_i32 s8, 0x1000, s8
	s_add_i32 s9, s5, 1
	s_sub_i32 s12, s8, s18
	s_cmp_ge_u32 s8, s18
	s_cselect_b32 s5, s9, s5
	s_cselect_b32 s8, s12, s8
	s_add_i32 s9, s5, 1
	s_cmp_ge_u32 s8, s18
	s_cselect_b32 s5, s9, s5
	s_xor_b32 s5, s5, s20
	s_sub_i32 s8, s5, s20
	s_cmp_lt_i32 s8, 1
	v_readfirstlane_b32 s66, v3
	s_cbranch_scc1 .LBB0_196
	s_mul_i32 s12, s62, 0xc000
	s_ashr_i32 s5, s7, 6
	s_lshl_b32 s9, s6, 3
	s_lshl_b32 s68, s62, 10
	s_add_i32 s67, s5, s9
	s_lshl_b64 s[6:7], s[12:13], 2
	s_mov_b32 s69, s13
	s_add_u32 s12, s61, s6
	s_addc_u32 s70, s63, s7
	s_lshl_b64 s[6:7], s[68:69], 2
	s_add_u32 s68, s64, s6
	s_addc_u32 s69, s66, s7
	s_ashr_i32 s6, s67, 31
	s_xor_b32 s64, s6, s20
	s_abs_i32 s6, s67
	s_mul_hi_u32 s7, s6, s65
	s_mul_i32 s20, s7, s18
	s_sub_i32 s6, s6, s20
	s_add_i32 s20, s7, 1
	s_sub_i32 s65, s6, s18
	s_cmp_ge_u32 s6, s18
	s_cselect_b32 s7, s20, s7
	s_cselect_b32 s6, s65, s6
	s_add_i32 s20, s7, 1
	s_cmp_ge_u32 s6, s18
	s_cselect_b32 s6, s20, s7
	s_xor_b32 s65, s6, s64
	s_sub_i32 s6, s65, s64
	s_mul_i32 s66, s6, 0x1800
	s_ashr_i32 s67, s66, 31
	s_lshl_b64 s[66:67], s[66:67], 2
	v_and_b32_e32 v16, 63, v0
	s_add_u32 s66, s12, s66
	s_addc_u32 s67, s70, s67
	v_lshlrev_b32_e32 v162, 4, v16
	v_lshl_add_u64 v[0:1], s[66:67], 0, v[162:163]
	v_and_b32_e32 v136, 63, v160
	v_lshlrev_b32_e32 v137, 5, v136
	v_lshlrev_b32_e32 v138, 4, v136
	v_lshlrev_b32_e32 v139, 3, v136
	v_add_u32_e32 v116, 0x0, v137
	v_add_u32_e32 v120, 0x0, v138
	v_mov_b32_e32 v121, 0
	v_add_u32_e32 v117, 0x10, v137
	v_add_u32_e32 v122, 0x10, v138
	v_mov_b32_e32 v123, 0
	v_add_u32_e32 v118, 0x800, v137
	v_add_u32_e32 v124, 0x800, v138
	v_mov_b32_e32 v125, 0
	v_add_u32_e32 v119, 0x810, v137
	v_add_u32_e32 v126, 0x810, v138
	v_mov_b32_e32 v127, 0
	v_mov_b32_e32 v128, v139
	v_mov_b32_e32 v129, 0
	v_add_u32_e32 v130, 0x400, v139
	v_mov_b32_e32 v131, 0
	v_add_co_u32_e32 v2, vcc, s46, v0
	s_mov_b64 s[34:35], 0x1000
	s_nop 0
	v_addc_co_u32_e32 v3, vcc, 0, v1, vcc
	v_lshl_add_u64 v[136:137], v[2:3], 0, v[120:121]
	global_load_dwordx4 v[18:21], v[136:137], off
	v_lshl_add_u64 v[0:1], v[0:1], 0, s[34:35]
	v_lshl_add_u64 v[136:137], v[0:1], 0, v[122:123]
	global_load_dwordx4 v[22:25], v[136:137], off
	v_lshl_add_u64 v[136:137], v[0:1], 0, v[124:125]
	global_load_dwordx4 v[26:29], v[136:137], off
	v_lshl_add_u64 v[136:137], v[0:1], 0, v[126:127]
	global_load_dwordx4 v[30:33], v[136:137], off
	global_load_dwordx4 v[34:37], v116, s[68:69]
	global_load_dwordx4 v[38:41], v117, s[68:69]
	global_load_dwordx4 v[42:45], v118, s[68:69]
	global_load_dwordx4 v[46:49], v119, s[68:69]
	s_nop 0
	global_load_dwordx4 v[0:3], v116, s[66:67]
	global_load_dwordx4 v[4:7], v117, s[66:67]
	global_load_dwordx4 v[8:11], v118, s[66:67]
	global_load_dwordx4 v[12:15], v119, s[66:67]
	s_ashr_i32 s7, s6, 31
	s_lshl_b64 s[68:69], s[6:7], 24
	s_mul_hi_i32 s67, s4, s6
	s_mul_i32 s66, s4, s6
	s_add_u32 s16, s16, s68
	s_addc_u32 s17, s17, s69
	s_lshl_b64 s[66:67], s[66:67], 2
	s_add_u32 s18, s0, s66
	s_addc_u32 s20, s1, s67
	s_lshl_b64 s[0:1], s[6:7], 23
	s_add_u32 s0, s61, s0
	s_mul_i32 s70, s6, s19
	s_addc_u32 s1, s63, s1
	s_lshl_b32 s6, s6, 10
	s_ashr_i32 s7, s6, 31
	s_lshl_b64 s[6:7], s[6:7], 2
	s_add_u32 s6, s61, s6
	s_addc_u32 s7, s63, s7
	v_cmp_lt_i32_e32 vcc, v228, v222
	v_xor_b32_e32 v50, 2, v221
	s_lshl_b32 s63, s19, 2
	v_cndmask_b32_e32 v17, v221, v228, vcc
	v_cmp_lt_i32_e32 vcc, v50, v222
	s_mov_b32 s12, 0
	v_lshlrev_b32_e32 v104, 2, v17
	v_cndmask_b32_e32 v50, v221, v50, vcc
	v_cmp_lt_i32_e32 vcc, v218, v222
	v_lshlrev_b32_e32 v105, 2, v50
	s_sub_i32 s78, s5, s70
	v_cndmask_b32_e32 v51, v221, v218, vcc
	v_cmp_lt_i32_e32 vcc, v219, v222
	v_lshlrev_b32_e32 v106, 2, v51
	v_lshlrev_b32_e32 v110, 4, v16
	v_cndmask_b32_e32 v52, v221, v219, vcc
	v_cmp_lt_i32_e32 vcc, v254, v222
	v_lshlrev_b32_e32 v107, 2, v52
	s_waitcnt vmcnt(0)
	v_pk_add_f32 v[24:25], v[24:25], 1.0 op_sel_hi:[1,0]
	v_cndmask_b32_e32 v53, v221, v254, vcc
	v_cmp_lt_i32_e32 vcc, v223, v222
	v_pk_add_f32 v[22:23], v[22:23], 1.0 op_sel_hi:[1,0]
	s_waitcnt vmcnt(9)
	v_pk_add_f32 v[28:29], v[28:29], 1.0 op_sel_hi:[1,0]
	v_cndmask_b32_e32 v54, v221, v223, vcc
	v_pk_add_f32 v[26:27], v[26:27], 1.0 op_sel_hi:[1,0]
	s_waitcnt vmcnt(8)
	v_pk_add_f32 v[32:33], v[32:33], 1.0 op_sel_hi:[1,0]
	v_pk_add_f32 v[18:19], v[18:19], 1.0 op_sel_hi:[1,0]
	v_pk_add_f32 v[20:21], v[20:21], 1.0 op_sel_hi:[1,0]
	s_waitcnt vmcnt(7)
	v_pk_mul_f32 v[82:83], v[34:35], v[18:19]
	v_lshl_add_u64 v[18:19], s[6:7], 0, v[162:163]
	s_mov_b64 s[6:7], 0x598000
	v_lshlrev_b32_e32 v162, 3, v16
	v_lshl_add_u64 v[96:97], v[18:19], 0, s[6:7]
	v_lshl_add_u64 v[18:19], s[0:1], 0, v[162:163]
	s_mov_b64 s[0:1], 0x6e00000
	v_lshl_add_u64 v[98:99], v[18:19], 0, s[0:1]
	s_sub_i32 s0, s64, s65
	s_add_i32 s1, s0, 1
	s_mul_i32 s1, s19, s1
	s_add_i32 s61, s5, s1
	s_add_i32 s1, s0, 2
	s_add_i32 s0, s0, 3
	v_pk_add_f32 v[30:31], v[30:31], 1.0 op_sel_hi:[1,0]
	s_mul_i32 s1, s19, s1
	s_mul_i32 s19, s19, s0
	v_lshlrev_b32_e32 v108, 2, v53
	v_lshlrev_b32_e32 v109, 2, v54
	v_pk_mul_f32 v[80:81], v[36:37], v[20:21]
	s_waitcnt vmcnt(6)
	v_pk_mul_f32 v[84:85], v[40:41], v[24:25]
	v_pk_mul_f32 v[86:87], v[38:39], v[22:23]
	s_waitcnt vmcnt(5)
	v_pk_mul_f32 v[88:89], v[44:45], v[28:29]
	v_pk_mul_f32 v[90:91], v[42:43], v[26:27]
	s_waitcnt vmcnt(4)
	v_pk_mul_f32 v[92:93], v[48:49], v[32:33]
	v_pk_mul_f32 v[94:95], v[46:47], v[30:31]
	s_add_i32 s76, s5, s1
	s_add_i32 s77, s5, s19
	s_branch .LBB0_164

; __device__ __forceinline__ unsigned pk2(float lo, float hi) { return f2bf(lo) | (f2bf(hi) << 16); }
; __device__ __forceinline__ void norm_mod_phase(const float* x, const float* x0src, size_t x0stride, float* h0buf, const float* g, const float* sh, const float* sc, bf16* XN, int gw, int NGW, int lane) {
;     ...
;     for (int k = 0; k < rpw; k += 4) {
;         f32x4 v[4][4];
; #pragma unroll
;         for (int r = 0; r < 4; ++r) { const int t = wi + wpb * (k + r); const bool t0 = t == 0;
;             const f32x4* xr = (const f32x4*)(t0 ? x0src + (size_t)b * x0stride : x + ((size_t)b * T + t) * D) + lane;
; #pragma unroll
;             for (int j = 0; j < 4; ++j) v[r][j] = xr[64 * j]; }
;         __builtin_amdgcn_sched_barrier(0);
; #pragma unroll
;         for (int r = 0; r < 4; ++r) { const int t = wi + wpb * (k + r); const bool t0 = t == 0; const size_t row = (size_t)b * T + t;
;             float ss = 0.f;
; #pragma unroll
;             for (int j = 0; j < 4; ++j) ss += (v[r][j].x * v[r][j].x + v[r][j].y * v[r][j].y) + (v[r][j].z * v[r][j].z + v[r][j].w * v[r][j].w);
;             const float rstd = 1.f / sqrtf(wave_sum(ss) * (1.f / D) + EPS);
; #pragma unroll
;             for (int j = 0; j < 4; ++j) { const int col = 4 * lane + 256 * j;
;                 const f32x4 h = v[r][j] * rstd * gm[j] + s0[j];
;                 v2u o; o.x = pk2(h.x, h.y); o.y = pk2(h.z, h.w);
;                 *(v2u*)(XN + row * D + col) = o;
.LBB0_164:
	s_add_i32 s0, s9, s78
	s_ashr_i32 s1, s0, 31
	s_lshl_b64 s[4:5], s[0:1], 12
	s_add_u32 s6, s16, s4
	s_addc_u32 s7, s17, s5
	s_cmp_eq_u32 s0, 0
	s_cselect_b64 s[72:73], -1, 0
	s_and_b64 s[4:5], s[72:73], exec
	s_cselect_b32 s74, s18, s6
	s_cselect_b32 s75, s20, s7
	s_add_i32 s70, s9, s61
	s_ashr_i32 s71, s70, 31
	s_lshl_b64 s[4:5], s[70:71], 12
	s_add_u32 s6, s16, s4
	s_addc_u32 s7, s17, s5
	s_cmp_eq_u32 s70, 0
	s_cselect_b64 s[68:69], -1, 0
	s_and_b64 s[4:5], s[68:69], exec
	s_cselect_b32 s80, s18, s6
	s_cselect_b32 s81, s20, s7
	s_add_i32 s66, s9, s76
	s_ashr_i32 s67, s66, 31
	s_lshl_b64 s[4:5], s[66:67], 12
	s_add_u32 s6, s16, s4
	s_addc_u32 s7, s17, s5
	s_cmp_eq_u32 s66, 0
	s_cselect_b64 s[64:65], -1, 0
	s_and_b64 s[4:5], s[64:65], exec
	s_cselect_b32 s82, s18, s6
	s_cselect_b32 s83, s20, s7
	s_add_i32 s6, s9, s77
	s_ashr_i32 s7, s6, 31
	s_lshl_b64 s[4:5], s[6:7], 12
	s_add_u32 s19, s16, s4
	s_addc_u32 s79, s17, s5
	s_cmp_eq_u32 s6, 0
	s_cselect_b64 s[4:5], -1, 0
	s_and_b64 s[84:85], s[4:5], exec
	s_cselect_b32 s84, s18, s19
	s_cselect_b32 s85, s20, s79
	global_load_dwordx4 v[76:79], v116, s[74:75]
	global_load_dwordx4 v[72:75], v117, s[74:75]
	global_load_dwordx4 v[68:71], v118, s[74:75]
	global_load_dwordx4 v[64:67], v119, s[74:75]
	global_load_dwordx4 v[60:63], v116, s[80:81]
	global_load_dwordx4 v[56:59], v117, s[80:81]
	global_load_dwordx4 v[52:55], v118, s[80:81]
	global_load_dwordx4 v[48:51], v119, s[80:81]
	global_load_dwordx4 v[44:47], v116, s[82:83]
	global_load_dwordx4 v[40:43], v117, s[82:83]
	global_load_dwordx4 v[36:39], v118, s[82:83]
	global_load_dwordx4 v[32:35], v119, s[82:83]
	global_load_dwordx4 v[28:31], v116, s[84:85]
	global_load_dwordx4 v[24:27], v117, s[84:85]
	global_load_dwordx4 v[20:23], v118, s[84:85]
	global_load_dwordx4 v[16:19], v119, s[84:85]
	s_lshl_b64 s[74:75], s[0:1], 11
	s_cmp_lg_u32 s0, 0
	s_waitcnt vmcnt(15)
	v_pk_mul_f32 v[100:101], v[78:79], v[78:79]
	v_pk_mul_f32 v[102:103], v[76:77], v[76:77]
	s_waitcnt vmcnt(12)
	v_mul_f32_e32 v111, v64, v64
	v_pk_mov_b32 v[112:113], v[102:103], v[100:101] op_sel:[1,0]
	v_mov_b32_e32 v103, v101
	v_pk_add_f32 v[100:101], v[112:113], v[102:103]
	v_pk_mul_f32 v[102:103], v[74:75], v[74:75]
	v_pk_mul_f32 v[112:113], v[72:73], v[72:73]
	v_pk_add_f32 v[100:101], v[100:101], v[100:101] op_sel:[0,1] op_sel_hi:[1,0]
	v_pk_mov_b32 v[114:115], v[112:113], v[102:103] op_sel:[1,0]
	v_mov_b32_e32 v113, v103
	v_pk_add_f32 v[102:103], v[114:115], v[112:113]
	v_mul_f32_e32 v112, v65, v65
	v_pk_add_f32 v[102:103], v[102:103], v[102:103] op_sel:[0,1] op_sel_hi:[1,0]
	v_mov_b32_e32 v101, v111
	v_mov_b32_e32 v103, v112
	v_pk_add_f32 v[100:101], v[100:101], v[102:103]
	v_mul_f32_e32 v102, v69, v69
	v_mul_f32_e32 v113, v66, v66
	v_pk_fma_f32 v[102:103], v[68:69], v[68:69], v[102:103] op_sel_hi:[1,1,0]
	v_mul_f32_e32 v112, v71, v71
	v_mul_f32_e32 v114, v67, v67
	v_mov_b32_e32 v103, v113
	v_pk_fma_f32 v[112:113], v[70:71], v[70:71], v[112:113] op_sel_hi:[1,1,0]
	s_nop 0
	v_mov_b32_e32 v113, v114
	v_pk_add_f32 v[102:103], v[102:103], v[112:113]
	s_nop 0
	v_pk_add_f32 v[100:101], v[100:101], v[102:103]
	s_nop 0
	v_add_f32_e32 v100, v100, v101
	ds_bpermute_b32 v101, v104, v100
	s_waitcnt lgkmcnt(0)
	v_add_f32_e32 v100, v100, v101
	ds_bpermute_b32 v101, v105, v100
	s_waitcnt lgkmcnt(0)
	v_add_f32_e32 v100, v100, v101
	ds_bpermute_b32 v101, v106, v100
	s_waitcnt lgkmcnt(0)
	v_add_f32_e32 v100, v100, v101
	ds_bpermute_b32 v101, v107, v100
	s_waitcnt lgkmcnt(0)
	v_add_f32_e32 v100, v100, v101
	ds_bpermute_b32 v101, v108, v100
	s_waitcnt lgkmcnt(0)
	v_add_f32_e32 v100, v100, v101
	ds_bpermute_b32 v101, v109, v100
	s_waitcnt lgkmcnt(0)
	v_add_f32_e32 v100, v100, v101
	v_fmamk_f32 v100, v100, 0x3a800000, v161
	v_mul_f32_e32 v101, 0x4f800000, v100
	v_cmp_gt_f32_e32 vcc, s58, v100
	s_nop 1
	v_cndmask_b32_e32 v100, v100, v101, vcc
	v_sqrt_f32_e32 v101, v100
	s_nop 0
	v_add_u32_e32 v102, -1, v101
	v_add_u32_e32 v103, 1, v101
	v_fma_f32 v111, -v102, v101, v100
	v_fma_f32 v112, -v103, v101, v100
	v_cmp_ge_f32_e64 s[0:1], 0, v111
	s_nop 1
	v_cndmask_b32_e64 v101, v101, v102, s[0:1]
	v_cmp_lt_f32_e64 s[0:1], 0, v112
	s_nop 1
	v_cndmask_b32_e64 v101, v101, v103, s[0:1]
	v_mul_f32_e32 v102, 0x37800000, v101
	v_cndmask_b32_e32 v101, v101, v102, vcc
	v_cmp_class_f32_e32 vcc, v100, v177
	s_nop 1
	v_cndmask_b32_e32 v100, v101, v100, vcc
	v_div_scale_f32 v101, s[0:1], v100, v100, 1.0
	v_rcp_f32_e32 v102, v101
	v_div_scale_f32 v103, vcc, 1.0, v100, 1.0
	v_fma_f32 v111, -v101, v102, 1.0
	v_fmac_f32_e32 v102, v111, v102
	v_mul_f32_e32 v111, v103, v102
	v_fma_f32 v112, -v101, v111, v103
	v_fmac_f32_e32 v111, v112, v102
	v_fma_f32 v101, -v101, v111, v103
	v_div_fmas_f32 v101, v101, v102, v111
	v_div_fixup_f32 v100, v101, v100, 1.0
	v_pk_mul_f32 v[76:77], v[76:77], v[100:101] op_sel_hi:[1,0]
	v_pk_mul_f32 v[78:79], v[78:79], v[100:101] op_sel_hi:[1,0]
	v_pk_fma_f32 v[76:77], v[82:83], v[76:77], v[0:1]
	v_pk_fma_f32 v[78:79], v[80:81], v[78:79], v[2:3]
	v_bfe_u32 v101, v76, 16, 1
	v_add3_u32 v101, v76, v101, s59
	v_bfe_u32 v102, v77, 16, 1
	v_lshrrev_b32_e32 v101, 16, v101
	v_add3_u32 v102, v77, v102, s59
	v_and_or_b32 v112, v102, s60, v101
	v_bfe_u32 v101, v78, 16, 1
	v_add3_u32 v101, v78, v101, s59
	v_bfe_u32 v102, v79, 16, 1
	v_lshrrev_b32_e32 v101, 16, v101
	v_add3_u32 v102, v79, v102, s59
	v_and_or_b32 v113, v102, s60, v101
	v_lshl_add_u64 v[102:103], v[98:99], 0, s[74:75]
	v_mov_b64_e32 v[140:141], v[112:113]
	s_cbranch_scc1 .LBB0_166
	v_lshl_add_u64 v[136:137], v[96:97], 0, v[120:121]
	global_store_dwordx4 v[136:137], v[76:79], off
; __device__ __forceinline__ unsigned pk2(float lo, float hi) { return f2bf(lo) | (f2bf(hi) << 16); }
; __device__ __forceinline__ void norm_mod_phase(const float* x, const float* x0src, size_t x0stride, float* h0buf, const float* g, const float* sh, const float* sc, bf16* XN, int gw, int NGW, int lane) {
;     ...
;         for (int r = 0; r < 4; ++r) { const int t = wi + wpb * (k + r); const bool t0 = t == 0;
;             const f32x4* xr = (const f32x4*)(t0 ? x0src + (size_t)b * x0stride : x + ((size_t)b * T + t) * D) + lane;
; #pragma unroll
;             for (int j = 0; j < 4; ++j) v[r][j] = xr[64 * j]; }
;         __builtin_amdgcn_sched_barrier(0);
; #pragma unroll
;         for (int r = 0; r < 4; ++r) { const int t = wi + wpb * (k + r); const bool t0 = t == 0; const size_t row = (size_t)b * T + t;
;             float ss = 0.f;
; #pragma unroll
;             for (int j = 0; j < 4; ++j) ss += (v[r][j].x * v[r][j].x + v[r][j].y * v[r][j].y) + (v[r][j].z * v[r][j].z + v[r][j].w * v[r][j].w);
;             const float rstd = 1.f / sqrtf(wave_sum(ss) * (1.f / D) + EPS);
; #pragma unroll
;             for (int j = 0; j < 4; ++j) { const int col = 4 * lane + 256 * j;
;                 const f32x4 h = v[r][j] * rstd * gm[j] + s0[j];
;                 v2u o; o.x = pk2(h.x, h.y); o.y = pk2(h.z, h.w);
;                 *(v2u*)(XN + row * D + col) = o;
;                 if (t0) *(f32x4*)(h0buf + b * D + col) = h; } }
.LBB0_166:
	v_mov_b32_e32 v101, v100
	v_pk_mul_f32 v[72:73], v[72:73], v[100:101]
	v_mov_b32_e32 v76, v100
	v_pk_fma_f32 v[72:73], v[86:87], v[72:73], v[4:5]
	v_mov_b32_e32 v77, v100
	v_bfe_u32 v78, v72, 16, 1
	v_pk_mul_f32 v[74:75], v[74:75], v[76:77]
	v_add3_u32 v78, v72, v78, s59
	v_bfe_u32 v79, v73, 16, 1
	v_pk_fma_f32 v[74:75], v[84:85], v[74:75], v[6:7]
	v_lshrrev_b32_e32 v78, 16, v78
	v_add3_u32 v79, v73, v79, s59
	v_and_or_b32 v78, v79, s60, v78
	v_bfe_u32 v79, v74, 16, 1
	v_add3_u32 v79, v74, v79, s59
	v_bfe_u32 v111, v75, 16, 1
	v_lshrrev_b32_e32 v79, 16, v79
	v_add3_u32 v111, v75, v111, s59
	v_and_or_b32 v79, v111, s60, v79
	v_cndmask_b32_e64 v111, 0, 1, s[72:73]
	v_cmp_ne_u32_e64 s[0:1], 1, v111
	s_andn2_b64 vcc, exec, s[72:73]
	v_mov_b64_e32 v[142:143], v[78:79]
	v_lshl_add_u64 v[136:137], v[102:103], 0, v[128:129]
	global_store_dwordx4 v[136:137], v[140:143], off
	s_cbranch_vccnz .LBB0_168
	v_lshl_add_u64 v[136:137], v[96:97], 0, v[122:123]
	global_store_dwordx4 v[136:137], v[72:75], off
.LBB0_168:
	v_pk_mul_f32 v[68:69], v[68:69], v[100:101]
	v_pk_mul_f32 v[70:71], v[70:71], v[76:77]
	v_pk_fma_f32 v[68:69], v[90:91], v[68:69], v[8:9]
	v_pk_fma_f32 v[70:71], v[88:89], v[70:71], v[10:11]
	v_bfe_u32 v72, v68, 16, 1
	v_add3_u32 v72, v68, v72, s59
	v_bfe_u32 v73, v69, 16, 1
	v_lshrrev_b32_e32 v72, 16, v72
	v_add3_u32 v73, v69, v73, s59
	v_and_or_b32 v72, v73, s60, v72
	v_bfe_u32 v73, v70, 16, 1
	v_add3_u32 v73, v70, v73, s59
	v_bfe_u32 v74, v71, 16, 1
	v_lshrrev_b32_e32 v73, 16, v73
	v_add3_u32 v74, v71, v74, s59
	v_and_or_b32 v73, v74, s60, v73
	s_and_b64 vcc, exec, s[0:1]
	v_mov_b64_e32 v[140:141], v[72:73]
	s_cbranch_vccnz .LBB0_170
	v_lshl_add_u64 v[136:137], v[96:97], 0, v[124:125]
	global_store_dwordx4 v[136:137], v[68:71], off
.LBB0_170:
	v_pk_mul_f32 v[64:65], v[64:65], v[100:101]
	s_nop 0
	v_mov_b32_e32 v68, v100
	v_mov_b32_e32 v69, v100
	v_pk_fma_f32 v[64:65], v[94:95], v[64:65], v[12:13]
	v_pk_mul_f32 v[66:67], v[66:67], v[68:69]
	v_bfe_u32 v68, v64, 16, 1
	v_add3_u32 v68, v64, v68, s59
	v_bfe_u32 v69, v65, 16, 1
	v_pk_fma_f32 v[66:67], v[92:93], v[66:67], v[14:15]
	v_lshrrev_b32_e32 v68, 16, v68
	v_add3_u32 v69, v65, v69, s59
	v_and_or_b32 v68, v69, s60, v68
	v_bfe_u32 v69, v66, 16, 1
	v_add3_u32 v69, v66, v69, s59
	v_bfe_u32 v70, v67, 16, 1
	v_lshrrev_b32_e32 v69, 16, v69
	v_add3_u32 v70, v67, v70, s59
	v_and_or_b32 v69, v70, s60, v69
	s_and_b64 vcc, exec, s[0:1]
	v_mov_b64_e32 v[142:143], v[68:69]
	v_lshl_add_u64 v[136:137], v[102:103], 0, v[130:131]
	global_store_dwordx4 v[136:137], v[140:143], off
	s_cbranch_vccnz .LBB0_172
	v_lshl_add_u64 v[136:137], v[96:97], 0, v[126:127]
	global_store_dwordx4 v[136:137], v[64:67], off
.LBB0_172:
	s_waitcnt vmcnt(13)
	s_nop 0
	v_pk_mul_f32 v[64:65], v[62:63], v[62:63]
	v_pk_mul_f32 v[66:67], v[60:61], v[60:61]
	s_nop 0
	v_pk_mov_b32 v[68:69], v[66:67], v[64:65] op_sel:[1,0]
	v_mov_b32_e32 v67, v65
	v_pk_add_f32 v[64:65], v[68:69], v[66:67]
	s_waitcnt vmcnt(12)
	v_pk_mul_f32 v[66:67], v[58:59], v[58:59]
	v_pk_mul_f32 v[68:69], v[56:57], v[56:57]
	v_pk_add_f32 v[64:65], v[64:65], v[64:65] op_sel:[0,1] op_sel_hi:[1,0]
	v_pk_mov_b32 v[70:71], v[68:69], v[66:67] op_sel:[1,0]
	v_mov_b32_e32 v69, v67
	v_pk_add_f32 v[66:67], v[70:71], v[68:69]
	s_waitcnt vmcnt(10)
	v_mul_f32_e32 v68, v48, v48
	v_mul_f32_e32 v69, v49, v49
	v_pk_add_f32 v[66:67], v[66:67], v[66:67] op_sel:[0,1] op_sel_hi:[1,0]
	v_mov_b32_e32 v65, v68
	v_mov_b32_e32 v67, v69
	v_pk_add_f32 v[64:65], v[64:65], v[66:67]
	v_mul_f32_e32 v66, v53, v53
	v_mul_f32_e32 v68, v55, v55
	v_mul_f32_e32 v70, v50, v50
	v_mul_f32_e32 v71, v51, v51
	v_pk_fma_f32 v[66:67], v[52:53], v[52:53], v[66:67] op_sel_hi:[1,1,0]
	v_pk_fma_f32 v[68:69], v[54:55], v[54:55], v[68:69] op_sel_hi:[1,1,0]
	v_mov_b32_e32 v67, v70
	v_mov_b32_e32 v69, v71
	v_pk_add_f32 v[66:67], v[66:67], v[68:69]
	s_nop 0
	v_pk_add_f32 v[64:65], v[64:65], v[66:67]
	s_nop 0
	v_add_f32_e32 v64, v64, v65
	ds_bpermute_b32 v65, v104, v64
	s_waitcnt lgkmcnt(0)
	v_add_f32_e32 v64, v64, v65
	ds_bpermute_b32 v65, v105, v64
	s_waitcnt lgkmcnt(0)
	v_add_f32_e32 v64, v64, v65
	ds_bpermute_b32 v65, v106, v64
	s_waitcnt lgkmcnt(0)
	v_add_f32_e32 v64, v64, v65
	ds_bpermute_b32 v65, v107, v64
	s_waitcnt lgkmcnt(0)
	v_add_f32_e32 v64, v64, v65
	ds_bpermute_b32 v65, v108, v64
	s_waitcnt lgkmcnt(0)
	v_add_f32_e32 v64, v64, v65
	ds_bpermute_b32 v65, v109, v64
	s_waitcnt lgkmcnt(0)
	v_add_f32_e32 v64, v64, v65
	v_fmamk_f32 v64, v64, 0x3a800000, v161
	v_mul_f32_e32 v65, 0x4f800000, v64
	v_cmp_gt_f32_e32 vcc, s58, v64
	s_nop 1
	v_cndmask_b32_e32 v64, v64, v65, vcc
	v_sqrt_f32_e32 v65, v64
	s_nop 0
	v_add_u32_e32 v66, -1, v65
	v_add_u32_e32 v67, 1, v65
	v_fma_f32 v68, -v66, v65, v64
	v_fma_f32 v69, -v67, v65, v64
	v_cmp_ge_f32_e64 s[0:1], 0, v68
	s_nop 1
	v_cndmask_b32_e64 v65, v65, v66, s[0:1]
	v_cmp_lt_f32_e64 s[0:1], 0, v69
	s_nop 1
	v_cndmask_b32_e64 v65, v65, v67, s[0:1]
	v_mul_f32_e32 v66, 0x37800000, v65
	v_cndmask_b32_e32 v65, v65, v66, vcc
	v_cmp_class_f32_e32 vcc, v64, v177
	s_nop 1
	v_cndmask_b32_e32 v64, v65, v64, vcc
	v_div_scale_f32 v65, s[0:1], v64, v64, 1.0
	v_rcp_f32_e32 v66, v65
	v_div_scale_f32 v67, vcc, 1.0, v64, 1.0
	s_lshl_b64 s[0:1], s[70:71], 11
	v_fma_f32 v68, -v65, v66, 1.0
	v_fmac_f32_e32 v66, v68, v66
	v_mul_f32_e32 v68, v67, v66
	v_fma_f32 v69, -v65, v68, v67
	v_fmac_f32_e32 v68, v69, v66
	v_fma_f32 v65, -v65, v68, v67
	v_div_fmas_f32 v65, v65, v66, v68
	v_div_fixup_f32 v64, v65, v64, 1.0
	v_pk_mul_f32 v[60:61], v[60:61], v[64:65] op_sel_hi:[1,0]
	v_pk_mul_f32 v[62:63], v[62:63], v[64:65] op_sel_hi:[1,0]
	v_pk_fma_f32 v[60:61], v[82:83], v[60:61], v[0:1]
	v_pk_fma_f32 v[62:63], v[80:81], v[62:63], v[2:3]
	v_bfe_u32 v65, v60, 16, 1
	v_add3_u32 v65, v60, v65, s59
	v_bfe_u32 v66, v61, 16, 1
	v_lshrrev_b32_e32 v65, 16, v65
	v_add3_u32 v66, v61, v66, s59
	v_and_or_b32 v68, v66, s60, v65
	v_bfe_u32 v65, v62, 16, 1
	v_add3_u32 v65, v62, v65, s59
	v_bfe_u32 v66, v63, 16, 1
	v_lshrrev_b32_e32 v65, 16, v65
	v_add3_u32 v66, v63, v66, s59
	v_and_or_b32 v69, v66, s60, v65
	v_cndmask_b32_e64 v65, 0, 1, s[68:69]
	v_lshl_add_u64 v[66:67], v[98:99], 0, s[0:1]
	v_cmp_ne_u32_e64 s[0:1], 1, v65
	s_andn2_b64 vcc, exec, s[68:69]
	v_mov_b64_e32 v[140:141], v[68:69]
	s_cbranch_vccnz .LBB0_174
	v_lshl_add_u64 v[136:137], v[96:97], 0, v[120:121]
	global_store_dwordx4 v[136:137], v[60:63], off
; __device__ __forceinline__ unsigned pk2(float lo, float hi) { return f2bf(lo) | (f2bf(hi) << 16); }
; __device__ __forceinline__ void norm_mod_phase(const float* x, const float* x0src, size_t x0stride, float* h0buf, const float* g, const float* sh, const float* sc, bf16* XN, int gw, int NGW, int lane) {
;     ...
;         for (int r = 0; r < 4; ++r) { const int t = wi + wpb * (k + r); const bool t0 = t == 0; const size_t row = (size_t)b * T + t;
;             float ss = 0.f;
; #pragma unroll
;             for (int j = 0; j < 4; ++j) ss += (v[r][j].x * v[r][j].x + v[r][j].y * v[r][j].y) + (v[r][j].z * v[r][j].z + v[r][j].w * v[r][j].w);
;             const float rstd = 1.f / sqrtf(wave_sum(ss) * (1.f / D) + EPS);
; #pragma unroll
;             for (int j = 0; j < 4; ++j) { const int col = 4 * lane + 256 * j;
;                 const f32x4 h = v[r][j] * rstd * gm[j] + s0[j];
;                 v2u o; o.x = pk2(h.x, h.y); o.y = pk2(h.z, h.w);
;                 *(v2u*)(XN + row * D + col) = o;
;                 if (t0) *(f32x4*)(h0buf + b * D + col) = h; } }
.LBB0_174:
	v_mov_b32_e32 v65, v64
	v_pk_mul_f32 v[56:57], v[56:57], v[64:65]
	v_mov_b32_e32 v60, v64
	v_pk_fma_f32 v[56:57], v[86:87], v[56:57], v[4:5]
	v_mov_b32_e32 v61, v64
	v_bfe_u32 v62, v56, 16, 1
	v_pk_mul_f32 v[58:59], v[58:59], v[60:61]
	v_add3_u32 v62, v56, v62, s59
	v_bfe_u32 v63, v57, 16, 1
	v_pk_fma_f32 v[58:59], v[84:85], v[58:59], v[6:7]
	v_lshrrev_b32_e32 v62, 16, v62
	v_add3_u32 v63, v57, v63, s59
	v_and_or_b32 v62, v63, s60, v62
	v_bfe_u32 v63, v58, 16, 1
	v_add3_u32 v63, v58, v63, s59
	v_bfe_u32 v68, v59, 16, 1
	v_lshrrev_b32_e32 v63, 16, v63
	v_add3_u32 v68, v59, v68, s59
	v_and_or_b32 v63, v68, s60, v63
	s_and_b64 vcc, exec, s[0:1]
	v_mov_b64_e32 v[142:143], v[62:63]
	v_lshl_add_u64 v[136:137], v[66:67], 0, v[128:129]
	global_store_dwordx4 v[136:137], v[140:143], off
	s_cbranch_vccnz .LBB0_176
	v_lshl_add_u64 v[136:137], v[96:97], 0, v[122:123]
	global_store_dwordx4 v[136:137], v[56:59], off
.LBB0_176:
	v_pk_mul_f32 v[52:53], v[52:53], v[64:65]
	v_pk_mul_f32 v[54:55], v[54:55], v[60:61]
	v_pk_fma_f32 v[52:53], v[90:91], v[52:53], v[8:9]
	v_pk_fma_f32 v[54:55], v[88:89], v[54:55], v[10:11]
	v_bfe_u32 v56, v52, 16, 1
	v_add3_u32 v56, v52, v56, s59
	v_bfe_u32 v57, v53, 16, 1
	v_lshrrev_b32_e32 v56, 16, v56
	v_add3_u32 v57, v53, v57, s59
	v_and_or_b32 v56, v57, s60, v56
	v_bfe_u32 v57, v54, 16, 1
	v_add3_u32 v57, v54, v57, s59
	v_bfe_u32 v58, v55, 16, 1
	v_lshrrev_b32_e32 v57, 16, v57
	v_add3_u32 v58, v55, v58, s59
	v_and_or_b32 v57, v58, s60, v57
	s_and_b64 vcc, exec, s[0:1]
	v_mov_b64_e32 v[140:141], v[56:57]
	s_cbranch_vccnz .LBB0_178
	v_lshl_add_u64 v[136:137], v[96:97], 0, v[124:125]
	global_store_dwordx4 v[136:137], v[52:55], off
.LBB0_178:
	v_pk_mul_f32 v[48:49], v[48:49], v[64:65]
	s_nop 0
	v_mov_b32_e32 v52, v64
	v_mov_b32_e32 v53, v64
	v_pk_fma_f32 v[48:49], v[94:95], v[48:49], v[12:13]
	v_pk_mul_f32 v[50:51], v[50:51], v[52:53]
	v_bfe_u32 v52, v48, 16, 1
	v_add3_u32 v52, v48, v52, s59
	v_bfe_u32 v53, v49, 16, 1
	v_pk_fma_f32 v[50:51], v[92:93], v[50:51], v[14:15]
	v_lshrrev_b32_e32 v52, 16, v52
	v_add3_u32 v53, v49, v53, s59
	v_and_or_b32 v52, v53, s60, v52
	v_bfe_u32 v53, v50, 16, 1
	v_add3_u32 v53, v50, v53, s59
	v_bfe_u32 v54, v51, 16, 1
	v_lshrrev_b32_e32 v53, 16, v53
	v_add3_u32 v54, v51, v54, s59
	v_and_or_b32 v53, v54, s60, v53
	s_and_b64 vcc, exec, s[0:1]
	v_mov_b64_e32 v[142:143], v[52:53]
	v_lshl_add_u64 v[136:137], v[66:67], 0, v[130:131]
	global_store_dwordx4 v[136:137], v[140:143], off
	s_cbranch_vccnz .LBB0_180
	v_lshl_add_u64 v[136:137], v[96:97], 0, v[126:127]
	global_store_dwordx4 v[136:137], v[48:51], off
.LBB0_180:
	s_waitcnt vmcnt(11)
	s_nop 0
	v_pk_mul_f32 v[48:49], v[46:47], v[46:47]
	v_pk_mul_f32 v[50:51], v[44:45], v[44:45]
	s_nop 0
	v_pk_mov_b32 v[52:53], v[50:51], v[48:49] op_sel:[1,0]
	v_mov_b32_e32 v51, v49
	v_pk_add_f32 v[48:49], v[52:53], v[50:51]
	s_waitcnt vmcnt(10)
	v_pk_mul_f32 v[50:51], v[42:43], v[42:43]
	v_pk_mul_f32 v[52:53], v[40:41], v[40:41]
	v_pk_add_f32 v[48:49], v[48:49], v[48:49] op_sel:[0,1] op_sel_hi:[1,0]
	v_pk_mov_b32 v[54:55], v[52:53], v[50:51] op_sel:[1,0]
	v_mov_b32_e32 v53, v51
	v_pk_add_f32 v[50:51], v[54:55], v[52:53]
	s_waitcnt vmcnt(8)
	v_mul_f32_e32 v52, v32, v32
	v_mul_f32_e32 v53, v33, v33
	v_pk_add_f32 v[50:51], v[50:51], v[50:51] op_sel:[0,1] op_sel_hi:[1,0]
	v_mov_b32_e32 v49, v52
	v_mov_b32_e32 v51, v53
	v_pk_add_f32 v[48:49], v[48:49], v[50:51]
	v_mul_f32_e32 v50, v37, v37
	v_mul_f32_e32 v52, v39, v39
	v_mul_f32_e32 v54, v34, v34
	v_mul_f32_e32 v55, v35, v35
	v_pk_fma_f32 v[50:51], v[36:37], v[36:37], v[50:51] op_sel_hi:[1,1,0]
	v_pk_fma_f32 v[52:53], v[38:39], v[38:39], v[52:53] op_sel_hi:[1,1,0]
	v_mov_b32_e32 v51, v54
	v_mov_b32_e32 v53, v55
	v_pk_add_f32 v[50:51], v[50:51], v[52:53]
	s_nop 0
	v_pk_add_f32 v[48:49], v[48:49], v[50:51]
	s_nop 0
	v_add_f32_e32 v48, v48, v49
	ds_bpermute_b32 v49, v104, v48
	s_waitcnt lgkmcnt(0)
	v_add_f32_e32 v48, v48, v49
	ds_bpermute_b32 v49, v105, v48
	s_waitcnt lgkmcnt(0)
	v_add_f32_e32 v48, v48, v49
	ds_bpermute_b32 v49, v106, v48
	s_waitcnt lgkmcnt(0)
	v_add_f32_e32 v48, v48, v49
	ds_bpermute_b32 v49, v107, v48
	s_waitcnt lgkmcnt(0)
	v_add_f32_e32 v48, v48, v49
	ds_bpermute_b32 v49, v108, v48
	s_waitcnt lgkmcnt(0)
	v_add_f32_e32 v48, v48, v49
	ds_bpermute_b32 v49, v109, v48
	s_waitcnt lgkmcnt(0)
	v_add_f32_e32 v48, v48, v49
	v_fmamk_f32 v48, v48, 0x3a800000, v161
	v_mul_f32_e32 v49, 0x4f800000, v48
	v_cmp_gt_f32_e32 vcc, s58, v48
	s_nop 1
	v_cndmask_b32_e32 v48, v48, v49, vcc
	v_sqrt_f32_e32 v49, v48
	s_nop 0
	v_add_u32_e32 v50, -1, v49
	v_add_u32_e32 v51, 1, v49
	v_fma_f32 v52, -v50, v49, v48
	v_fma_f32 v53, -v51, v49, v48
	v_cmp_ge_f32_e64 s[0:1], 0, v52
	s_nop 1
	v_cndmask_b32_e64 v49, v49, v50, s[0:1]
	v_cmp_lt_f32_e64 s[0:1], 0, v53
	s_nop 1
	v_cndmask_b32_e64 v49, v49, v51, s[0:1]
	v_mul_f32_e32 v50, 0x37800000, v49
	v_cndmask_b32_e32 v49, v49, v50, vcc
	v_cmp_class_f32_e32 vcc, v48, v177
	s_nop 1
	v_cndmask_b32_e32 v48, v49, v48, vcc
	v_div_scale_f32 v49, s[0:1], v48, v48, 1.0
	v_rcp_f32_e32 v50, v49
	v_div_scale_f32 v51, vcc, 1.0, v48, 1.0
	s_lshl_b64 s[0:1], s[66:67], 11
	v_fma_f32 v52, -v49, v50, 1.0
	v_fmac_f32_e32 v50, v52, v50
	v_mul_f32_e32 v52, v51, v50
	v_fma_f32 v53, -v49, v52, v51
	v_fmac_f32_e32 v52, v53, v50
	v_fma_f32 v49, -v49, v52, v51
	v_div_fmas_f32 v49, v49, v50, v52
	v_div_fixup_f32 v48, v49, v48, 1.0
	v_pk_mul_f32 v[44:45], v[44:45], v[48:49] op_sel_hi:[1,0]
	v_pk_mul_f32 v[46:47], v[46:47], v[48:49] op_sel_hi:[1,0]
	v_pk_fma_f32 v[44:45], v[82:83], v[44:45], v[0:1]
	v_pk_fma_f32 v[46:47], v[80:81], v[46:47], v[2:3]
	v_bfe_u32 v49, v44, 16, 1
	v_add3_u32 v49, v44, v49, s59
	v_bfe_u32 v50, v45, 16, 1
	v_lshrrev_b32_e32 v49, 16, v49
	v_add3_u32 v50, v45, v50, s59
	v_and_or_b32 v52, v50, s60, v49
	v_bfe_u32 v49, v46, 16, 1
	v_add3_u32 v49, v46, v49, s59
	v_bfe_u32 v50, v47, 16, 1
	v_lshrrev_b32_e32 v49, 16, v49
	v_add3_u32 v50, v47, v50, s59
	v_and_or_b32 v53, v50, s60, v49
	v_cndmask_b32_e64 v49, 0, 1, s[64:65]
	v_lshl_add_u64 v[50:51], v[98:99], 0, s[0:1]
	v_cmp_ne_u32_e64 s[0:1], 1, v49
	s_andn2_b64 vcc, exec, s[64:65]
	v_mov_b64_e32 v[140:141], v[52:53]
	s_cbranch_vccnz .LBB0_182
	v_lshl_add_u64 v[136:137], v[96:97], 0, v[120:121]
	global_store_dwordx4 v[136:137], v[44:47], off
; __device__ __forceinline__ unsigned pk2(float lo, float hi) { return f2bf(lo) | (f2bf(hi) << 16); }
; __device__ __forceinline__ void norm_mod_phase(const float* x, const float* x0src, size_t x0stride, float* h0buf, const float* g, const float* sh, const float* sc, bf16* XN, int gw, int NGW, int lane) {
;     ...
;         for (int r = 0; r < 4; ++r) { const int t = wi + wpb * (k + r); const bool t0 = t == 0; const size_t row = (size_t)b * T + t;
;             float ss = 0.f;
; #pragma unroll
;             for (int j = 0; j < 4; ++j) ss += (v[r][j].x * v[r][j].x + v[r][j].y * v[r][j].y) + (v[r][j].z * v[r][j].z + v[r][j].w * v[r][j].w);
;             const float rstd = 1.f / sqrtf(wave_sum(ss) * (1.f / D) + EPS);
; #pragma unroll
;             for (int j = 0; j < 4; ++j) { const int col = 4 * lane + 256 * j;
;                 const f32x4 h = v[r][j] * rstd * gm[j] + s0[j];
;                 v2u o; o.x = pk2(h.x, h.y); o.y = pk2(h.z, h.w);
;                 *(v2u*)(XN + row * D + col) = o;
;                 if (t0) *(f32x4*)(h0buf + b * D + col) = h; } }
.LBB0_182:
	v_mov_b32_e32 v49, v48
	v_pk_mul_f32 v[40:41], v[40:41], v[48:49]
	v_mov_b32_e32 v44, v48
	v_pk_fma_f32 v[40:41], v[86:87], v[40:41], v[4:5]
	v_mov_b32_e32 v45, v48
	v_bfe_u32 v46, v40, 16, 1
	v_pk_mul_f32 v[42:43], v[42:43], v[44:45]
	v_add3_u32 v46, v40, v46, s59
	v_bfe_u32 v47, v41, 16, 1
	v_pk_fma_f32 v[42:43], v[84:85], v[42:43], v[6:7]
	v_lshrrev_b32_e32 v46, 16, v46
	v_add3_u32 v47, v41, v47, s59
	v_and_or_b32 v46, v47, s60, v46
	v_bfe_u32 v47, v42, 16, 1
	v_add3_u32 v47, v42, v47, s59
	v_bfe_u32 v52, v43, 16, 1
	v_lshrrev_b32_e32 v47, 16, v47
	v_add3_u32 v52, v43, v52, s59
	v_and_or_b32 v47, v52, s60, v47
	s_and_b64 vcc, exec, s[0:1]
	v_mov_b64_e32 v[142:143], v[46:47]
	v_lshl_add_u64 v[136:137], v[50:51], 0, v[128:129]
	global_store_dwordx4 v[136:137], v[140:143], off
	s_cbranch_vccnz .LBB0_184
	v_lshl_add_u64 v[136:137], v[96:97], 0, v[122:123]
	global_store_dwordx4 v[136:137], v[40:43], off
.LBB0_184:
	v_pk_mul_f32 v[36:37], v[36:37], v[48:49]
	v_pk_mul_f32 v[38:39], v[38:39], v[44:45]
	v_pk_fma_f32 v[36:37], v[90:91], v[36:37], v[8:9]
	v_pk_fma_f32 v[38:39], v[88:89], v[38:39], v[10:11]
	v_bfe_u32 v40, v36, 16, 1
	v_add3_u32 v40, v36, v40, s59
	v_bfe_u32 v41, v37, 16, 1
	v_lshrrev_b32_e32 v40, 16, v40
	v_add3_u32 v41, v37, v41, s59
	v_and_or_b32 v40, v41, s60, v40
	v_bfe_u32 v41, v38, 16, 1
	v_add3_u32 v41, v38, v41, s59
	v_bfe_u32 v42, v39, 16, 1
	v_lshrrev_b32_e32 v41, 16, v41
	v_add3_u32 v42, v39, v42, s59
	v_and_or_b32 v41, v42, s60, v41
	s_and_b64 vcc, exec, s[0:1]
	v_mov_b64_e32 v[140:141], v[40:41]
	s_cbranch_vccnz .LBB0_186
	v_lshl_add_u64 v[136:137], v[96:97], 0, v[124:125]
	global_store_dwordx4 v[136:137], v[36:39], off
.LBB0_186:
	v_pk_mul_f32 v[32:33], v[32:33], v[48:49]
	s_nop 0
	v_mov_b32_e32 v36, v48
	v_mov_b32_e32 v37, v48
	v_pk_fma_f32 v[32:33], v[94:95], v[32:33], v[12:13]
	v_pk_mul_f32 v[34:35], v[34:35], v[36:37]
	v_bfe_u32 v36, v32, 16, 1
	v_add3_u32 v36, v32, v36, s59
	v_bfe_u32 v37, v33, 16, 1
	v_pk_fma_f32 v[34:35], v[92:93], v[34:35], v[14:15]
	v_lshrrev_b32_e32 v36, 16, v36
	v_add3_u32 v37, v33, v37, s59
	v_and_or_b32 v36, v37, s60, v36
	v_bfe_u32 v37, v34, 16, 1
	v_add3_u32 v37, v34, v37, s59
	v_bfe_u32 v38, v35, 16, 1
	v_lshrrev_b32_e32 v37, 16, v37
	v_add3_u32 v38, v35, v38, s59
	v_and_or_b32 v37, v38, s60, v37
	s_and_b64 vcc, exec, s[0:1]
	v_mov_b64_e32 v[142:143], v[36:37]
	v_lshl_add_u64 v[136:137], v[50:51], 0, v[130:131]
	global_store_dwordx4 v[136:137], v[140:143], off
	s_cbranch_vccnz .LBB0_188
	v_lshl_add_u64 v[136:137], v[96:97], 0, v[126:127]
	global_store_dwordx4 v[136:137], v[32:35], off
.LBB0_188:
	s_waitcnt vmcnt(9)
	s_nop 0
	v_pk_mul_f32 v[32:33], v[30:31], v[30:31]
	v_pk_mul_f32 v[34:35], v[28:29], v[28:29]
	s_nop 0
	v_pk_mov_b32 v[36:37], v[34:35], v[32:33] op_sel:[1,0]
	v_mov_b32_e32 v35, v33
	v_pk_add_f32 v[32:33], v[36:37], v[34:35]
	s_waitcnt vmcnt(8)
	v_pk_mul_f32 v[34:35], v[26:27], v[26:27]
	v_pk_mul_f32 v[36:37], v[24:25], v[24:25]
	v_pk_add_f32 v[32:33], v[32:33], v[32:33] op_sel:[0,1] op_sel_hi:[1,0]
	v_pk_mov_b32 v[38:39], v[36:37], v[34:35] op_sel:[1,0]
	v_mov_b32_e32 v37, v35
	v_pk_add_f32 v[34:35], v[38:39], v[36:37]
	s_waitcnt vmcnt(6)
	v_mul_f32_e32 v36, v16, v16
	v_mul_f32_e32 v37, v17, v17
	v_pk_add_f32 v[34:35], v[34:35], v[34:35] op_sel:[0,1] op_sel_hi:[1,0]
	v_mov_b32_e32 v33, v36
	v_mov_b32_e32 v35, v37
	v_pk_add_f32 v[32:33], v[32:33], v[34:35]
	v_mul_f32_e32 v34, v21, v21
	v_mul_f32_e32 v36, v23, v23
	v_mul_f32_e32 v38, v18, v18
	v_mul_f32_e32 v39, v19, v19
	v_pk_fma_f32 v[34:35], v[20:21], v[20:21], v[34:35] op_sel_hi:[1,1,0]
	v_pk_fma_f32 v[36:37], v[22:23], v[22:23], v[36:37] op_sel_hi:[1,1,0]
	v_mov_b32_e32 v35, v38
	v_mov_b32_e32 v37, v39
	v_pk_add_f32 v[34:35], v[34:35], v[36:37]
	s_nop 0
	v_pk_add_f32 v[32:33], v[32:33], v[34:35]
	s_nop 0
	v_add_f32_e32 v32, v32, v33
	ds_bpermute_b32 v33, v104, v32
	s_waitcnt lgkmcnt(0)
	v_add_f32_e32 v32, v32, v33
	ds_bpermute_b32 v33, v105, v32
	s_waitcnt lgkmcnt(0)
	v_add_f32_e32 v32, v32, v33
	ds_bpermute_b32 v33, v106, v32
	s_waitcnt lgkmcnt(0)
	v_add_f32_e32 v32, v32, v33
	ds_bpermute_b32 v33, v107, v32
	s_waitcnt lgkmcnt(0)
	v_add_f32_e32 v32, v32, v33
	ds_bpermute_b32 v33, v108, v32
	s_waitcnt lgkmcnt(0)
	v_add_f32_e32 v32, v32, v33
	ds_bpermute_b32 v33, v109, v32
	s_waitcnt lgkmcnt(0)
	v_add_f32_e32 v32, v32, v33
	v_fmamk_f32 v32, v32, 0x3a800000, v161
	v_mul_f32_e32 v33, 0x4f800000, v32
	v_cmp_gt_f32_e32 vcc, s58, v32
	s_nop 1
	v_cndmask_b32_e32 v32, v32, v33, vcc
	v_sqrt_f32_e32 v33, v32
	s_nop 0
	v_add_u32_e32 v34, -1, v33
	v_add_u32_e32 v35, 1, v33
	v_fma_f32 v36, -v34, v33, v32
	v_fma_f32 v37, -v35, v33, v32
	v_cmp_ge_f32_e64 s[0:1], 0, v36
	s_nop 1
	v_cndmask_b32_e64 v33, v33, v34, s[0:1]
	v_cmp_lt_f32_e64 s[0:1], 0, v37
	s_nop 1
	v_cndmask_b32_e64 v33, v33, v35, s[0:1]
	v_mul_f32_e32 v34, 0x37800000, v33
	v_cndmask_b32_e32 v33, v33, v34, vcc
	v_cmp_class_f32_e32 vcc, v32, v177
	s_nop 1
	v_cndmask_b32_e32 v32, v33, v32, vcc
	v_div_scale_f32 v33, s[0:1], v32, v32, 1.0
	v_rcp_f32_e32 v34, v33
	v_div_scale_f32 v35, vcc, 1.0, v32, 1.0
	s_lshl_b64 s[0:1], s[6:7], 11
	v_fma_f32 v36, -v33, v34, 1.0
	v_fmac_f32_e32 v34, v36, v34
	v_mul_f32_e32 v36, v35, v34
	v_fma_f32 v37, -v33, v36, v35
	v_fmac_f32_e32 v36, v37, v34
	v_fma_f32 v33, -v33, v36, v35
	v_div_fmas_f32 v33, v33, v34, v36
	v_div_fixup_f32 v32, v33, v32, 1.0
	v_pk_mul_f32 v[28:29], v[28:29], v[32:33] op_sel_hi:[1,0]
	v_pk_mul_f32 v[30:31], v[30:31], v[32:33] op_sel_hi:[1,0]
	v_pk_fma_f32 v[28:29], v[82:83], v[28:29], v[0:1]
	v_pk_fma_f32 v[30:31], v[80:81], v[30:31], v[2:3]
	v_bfe_u32 v33, v28, 16, 1
	v_add3_u32 v33, v28, v33, s59
	v_bfe_u32 v34, v29, 16, 1
	v_lshrrev_b32_e32 v33, 16, v33
	v_add3_u32 v34, v29, v34, s59
	v_and_or_b32 v36, v34, s60, v33
	v_bfe_u32 v33, v30, 16, 1
	v_add3_u32 v33, v30, v33, s59
	v_bfe_u32 v34, v31, 16, 1
	v_lshrrev_b32_e32 v33, 16, v33
	v_add3_u32 v34, v31, v34, s59
	v_and_or_b32 v37, v34, s60, v33
	v_cndmask_b32_e64 v33, 0, 1, s[4:5]
	v_lshl_add_u64 v[34:35], v[98:99], 0, s[0:1]
	v_cmp_ne_u32_e64 s[0:1], 1, v33
	s_andn2_b64 vcc, exec, s[4:5]
	v_mov_b64_e32 v[140:141], v[36:37]
	s_cbranch_vccnz .LBB0_190
	v_lshl_add_u64 v[136:137], v[96:97], 0, v[120:121]
	global_store_dwordx4 v[136:137], v[28:31], off
; __device__ __forceinline__ unsigned pk2(float lo, float hi) { return f2bf(lo) | (f2bf(hi) << 16); }
; __device__ __forceinline__ void norm_mod_phase(const float* x, const float* x0src, size_t x0stride, float* h0buf, const float* g, const float* sh, const float* sc, bf16* XN, int gw, int NGW, int lane) {
;     ...
;             for (int j = 0; j < 4; ++j) { const int col = 4 * lane + 256 * j;
;                 const f32x4 h = v[r][j] * rstd * gm[j] + s0[j];
;                 v2u o; o.x = pk2(h.x, h.y); o.y = pk2(h.z, h.w);
;                 *(v2u*)(XN + row * D + col) = o;
;                 if (t0) *(f32x4*)(h0buf + b * D + col) = h; } }
;     }
.LBB0_190:
	v_mov_b32_e32 v33, v32
	v_pk_mul_f32 v[24:25], v[24:25], v[32:33]
	v_mov_b32_e32 v28, v32
	v_pk_fma_f32 v[24:25], v[86:87], v[24:25], v[4:5]
	v_mov_b32_e32 v29, v32
	v_bfe_u32 v30, v24, 16, 1
	v_pk_mul_f32 v[26:27], v[26:27], v[28:29]
	v_add3_u32 v30, v24, v30, s59
	v_bfe_u32 v31, v25, 16, 1
	v_pk_fma_f32 v[26:27], v[84:85], v[26:27], v[6:7]
	v_lshrrev_b32_e32 v30, 16, v30
	v_add3_u32 v31, v25, v31, s59
	v_and_or_b32 v30, v31, s60, v30
	v_bfe_u32 v31, v26, 16, 1
	v_add3_u32 v31, v26, v31, s59
	v_bfe_u32 v36, v27, 16, 1
	v_lshrrev_b32_e32 v31, 16, v31
	v_add3_u32 v36, v27, v36, s59
	v_and_or_b32 v31, v36, s60, v31
	s_and_b64 vcc, exec, s[0:1]
	v_mov_b64_e32 v[142:143], v[30:31]
	v_lshl_add_u64 v[136:137], v[34:35], 0, v[128:129]
	global_store_dwordx4 v[136:137], v[140:143], off
	s_cbranch_vccnz .LBB0_192
	v_lshl_add_u64 v[136:137], v[96:97], 0, v[122:123]
	global_store_dwordx4 v[136:137], v[24:27], off
.LBB0_192:
	v_pk_mul_f32 v[20:21], v[20:21], v[32:33]
	v_pk_mul_f32 v[22:23], v[22:23], v[28:29]
	v_pk_fma_f32 v[20:21], v[90:91], v[20:21], v[8:9]
	v_pk_fma_f32 v[22:23], v[88:89], v[22:23], v[10:11]
	v_bfe_u32 v24, v20, 16, 1
	v_add3_u32 v24, v20, v24, s59
	v_bfe_u32 v25, v21, 16, 1
	v_lshrrev_b32_e32 v24, 16, v24
	v_add3_u32 v25, v21, v25, s59
	v_and_or_b32 v24, v25, s60, v24
	v_bfe_u32 v25, v22, 16, 1
	v_add3_u32 v25, v22, v25, s59
	v_bfe_u32 v26, v23, 16, 1
	v_lshrrev_b32_e32 v25, 16, v25
	v_add3_u32 v26, v23, v26, s59
	v_and_or_b32 v25, v26, s60, v25
	s_and_b64 vcc, exec, s[0:1]
	v_mov_b64_e32 v[140:141], v[24:25]
	s_cbranch_vccnz .LBB0_194
	v_lshl_add_u64 v[136:137], v[96:97], 0, v[124:125]
	global_store_dwordx4 v[136:137], v[20:23], off
.LBB0_194:
	v_pk_mul_f32 v[16:17], v[16:17], v[32:33]
	s_nop 0
	v_mov_b32_e32 v20, v32
	v_mov_b32_e32 v21, v32
	v_pk_fma_f32 v[16:17], v[94:95], v[16:17], v[12:13]
	v_pk_mul_f32 v[18:19], v[18:19], v[20:21]
	v_bfe_u32 v20, v16, 16, 1
	v_add3_u32 v20, v16, v20, s59
	v_bfe_u32 v21, v17, 16, 1
	v_pk_fma_f32 v[18:19], v[92:93], v[18:19], v[14:15]
	v_lshrrev_b32_e32 v20, 16, v20
	v_add3_u32 v21, v17, v21, s59
	v_and_or_b32 v20, v21, s60, v20
	v_bfe_u32 v21, v18, 16, 1
	v_add3_u32 v21, v18, v21, s59
	v_bfe_u32 v22, v19, 16, 1
	v_lshrrev_b32_e32 v21, 16, v21
	v_add3_u32 v22, v19, v22, s59
	v_and_or_b32 v21, v22, s60, v21
	s_and_b64 vcc, exec, s[0:1]
	v_mov_b64_e32 v[142:143], v[20:21]
	v_lshl_add_u64 v[136:137], v[34:35], 0, v[130:131]
	global_store_dwordx4 v[136:137], v[140:143], off
	s_cbranch_vccnz .LBB0_163
	v_lshl_add_u64 v[136:137], v[96:97], 0, v[126:127]
	global_store_dwordx4 v[136:137], v[16:19], off
	s_branch .LBB0_163

; __device__ __forceinline__ void norm_mod_phase(const float* x, const float* x0src, size_t x0stride, float* h0buf, const float* g, const float* sh, const float* sc, bf16* XN, int gw, int NGW, int lane) {
;     const int wpb = NGW / BATCH, rpw = T / wpb;
;     const int b = gw / wpb, wi = gw - b * wpb;
;     f32x4 gm[4], s0[4];
; #pragma unroll
;     for (int j = 0; j < 4; ++j) { const int col = 4 * lane + 256 * j; gm[j] = *(const f32x4*)(g + col) * (*(const f32x4*)(sc + b * NMOD + col) + 1.f); s0[j] = *(const f32x4*)(sh + b * NMOD + col); }
.LBB0_1138:
	s_cmp_le_i32 s28, s8
	s_cselect_b64 s[2:3], -1, 0
	s_and_b64 s[0:1], s[2:3], s[0:1]
	s_andn2_b64 vcc, exec, s[0:1]
	s_cbranch_vccnz .LBB0_1174
	s_mov_b32 s4, s30
	s_mov_b32 s1, s10
	v_readlane_b32 s0, v255, 0
	v_readlane_b32 s3, v255, 11
	v_mov_b32_e32 v0, v160
	v_mov_b32_e32 v1, s0
	s_abs_i32 s0, s4
	v_mov_b32_e32 v6, s3
	ds_read2_b64 v[2:5], v1 offset1:1
	ds_read_b64 v[6:7], v6
	v_cvt_f32_u32_e32 v1, s0
	s_sub_i32 s7, 0, s0
	s_ashr_i32 s18, s4, 31
	v_readfirstlane_b32 s2, v0
	v_rcp_iflag_f32_e32 v1, v1
	s_waitcnt lgkmcnt(0)
	v_readfirstlane_b32 s5, v4
	v_readfirstlane_b32 s6, v5
	v_readfirstlane_b32 s16, v2
	v_mul_f32_e32 v1, 0x4f7ffffe, v1
	v_cvt_u32_f32_e32 v1, v1
	v_readfirstlane_b32 s17, v3
	v_readfirstlane_b32 s3, v6
	v_readfirstlane_b32 s20, v7
	v_readfirstlane_b32 s19, v1
	s_mul_i32 s7, s7, s19
	s_mul_hi_u32 s7, s19, s7
	s_add_i32 s19, s19, s7
	s_lshr_b32 s7, s19, 20
	s_mul_i32 s8, s7, s0
	s_sub_i32 s8, 0x1000, s8
	s_add_i32 s9, s7, 1
	s_sub_i32 s12, s8, s0
	s_cmp_ge_u32 s8, s0
	s_cselect_b32 s7, s9, s7
	s_cselect_b32 s8, s12, s8
	s_add_i32 s9, s7, 1
	s_cmp_ge_u32 s8, s0
	s_cselect_b32 s7, s9, s7
	s_xor_b32 s7, s7, s18
	s_sub_i32 s8, s7, s18
	s_cmp_lt_i32 s8, 1
	s_cbranch_scc1 .LBB0_1174
	s_mul_i32 s12, s62, 0xc000
	s_ashr_i32 s7, s2, 6
	s_lshl_b32 s9, s1, 3
	s_lshl_b32 s64, s62, 10
	s_add_i32 s1, s7, s9
	s_lshl_b64 s[66:67], s[12:13], 2
	s_mov_b32 s65, s13
	s_add_u32 s12, s5, s66
	s_addc_u32 s34, s6, s67
	s_lshl_b64 s[64:65], s[64:65], 2
	s_add_u32 s2, s3, s64
	s_addc_u32 s3, s20, s65
	s_ashr_i32 s20, s1, 31
	s_abs_i32 s1, s1
	s_mul_hi_u32 s19, s1, s19
	s_xor_b32 s18, s20, s18
	s_mul_i32 s20, s19, s0
	s_sub_i32 s1, s1, s20
	s_add_i32 s20, s19, 1
	s_sub_i32 s35, s1, s0
	s_cmp_ge_u32 s1, s0
	s_cselect_b32 s19, s20, s19
	s_cselect_b32 s1, s35, s1
	s_add_i32 s20, s19, 1
	s_cmp_ge_u32 s1, s0
	s_cselect_b32 s0, s20, s19
	s_xor_b32 s63, s0, s18
	s_sub_i32 s0, s63, s18
	s_mul_i32 s64, s0, 0x1800
	s_ashr_i32 s65, s64, 31
	s_lshl_b64 s[64:65], s[64:65], 2
	v_and_b32_e32 v16, 63, v0
	s_add_u32 s64, s12, s64
	s_addc_u32 s65, s34, s65
	v_lshlrev_b32_e32 v162, 4, v16
	v_and_b32_e32 v136, 63, v160
	v_lshlrev_b32_e32 v137, 5, v136
	v_lshlrev_b32_e32 v138, 4, v136
	v_lshlrev_b32_e32 v139, 3, v136
	v_add_u32_e32 v116, 0x0, v137
	v_add_u32_e32 v120, 0x0, v138
	v_mov_b32_e32 v121, 0
	v_add_u32_e32 v117, 0x10, v137
	v_add_u32_e32 v122, 0x10, v138
	v_mov_b32_e32 v123, 0
	v_add_u32_e32 v118, 0x800, v137
	v_add_u32_e32 v124, 0x800, v138
	v_mov_b32_e32 v125, 0
	v_add_u32_e32 v119, 0x810, v137
	v_add_u32_e32 v126, 0x810, v138
	v_mov_b32_e32 v127, 0
	v_mov_b32_e32 v128, v139
	v_mov_b32_e32 v129, 0
	v_add_u32_e32 v130, 0x400, v139
	v_mov_b32_e32 v131, 0
	v_lshl_add_u64 v[8:9], s[64:65], 0, v[162:163]
	s_movk_i32 s1, 0x4000
	v_add_co_u32_e32 v4, vcc, s1, v8
	global_load_dwordx4 v[0:3], v116, s[2:3]
	s_nop 0
	v_addc_co_u32_e32 v5, vcc, 0, v9, vcc
	v_lshl_add_u64 v[136:137], v[4:5], 0, v[120:121]
	global_load_dwordx4 v[4:7], v[136:137], off
	s_movk_i32 s1, 0x3000
	s_mov_b64 s[64:65], 0x4000
	v_lshl_add_u64 v[18:19], v[8:9], 0, s[64:65]
	s_mov_b64 s[64:65], 0x3000
	v_lshl_add_u64 v[22:23], v[8:9], 0, s[64:65]
	s_mul_i32 s19, s0, s4
	s_mov_b32 s12, 0
	v_lshlrev_b32_e32 v110, 4, v16
	s_waitcnt vmcnt(0)
	v_pk_add_f32 v[4:5], v[4:5], 1.0 op_sel_hi:[1,0]
	s_nop 0
	v_pk_mul_f32 v[82:83], v[0:1], v[4:5]
	v_add_co_u32_e32 v0, vcc, s1, v8
	v_pk_add_f32 v[6:7], v[6:7], 1.0 op_sel_hi:[1,0]
	s_nop 0
	v_addc_co_u32_e32 v1, vcc, 0, v9, vcc
	v_pk_mul_f32 v[80:81], v[2:3], v[6:7]
	v_lshl_add_u64 v[136:137], v[0:1], 0, v[120:121]
	global_load_dwordx4 v[0:3], v[136:137], off
	s_nop 0
	global_load_dwordx4 v[4:7], v117, s[2:3]
	v_lshl_add_u64 v[136:137], v[18:19], 0, v[122:123]
	global_load_dwordx4 v[8:11], v[136:137], off
	s_ashr_i32 s1, s0, 31
	v_cmp_lt_i32_e32 vcc, v228, v222
	s_waitcnt vmcnt(0)
	v_pk_add_f32 v[10:11], v[10:11], 1.0 op_sel_hi:[1,0]
	v_pk_add_f32 v[8:9], v[8:9], 1.0 op_sel_hi:[1,0]
	v_pk_mul_f32 v[84:85], v[6:7], v[10:11]
	v_pk_mul_f32 v[86:87], v[4:5], v[8:9]
	v_lshl_add_u64 v[136:137], v[22:23], 0, v[122:123]
	global_load_dwordx4 v[4:7], v[136:137], off
	global_load_dwordx4 v[8:11], v118, s[2:3]
	v_lshl_add_u64 v[136:137], v[18:19], 0, v[124:125]
	global_load_dwordx4 v[12:15], v[136:137], off
	v_cndmask_b32_e32 v17, v221, v228, vcc
	v_lshlrev_b32_e32 v104, 2, v17
	v_xor_b32_e32 v17, 2, v221
	v_cmp_lt_i32_e32 vcc, v17, v222
	s_waitcnt vmcnt(0)
	v_pk_add_f32 v[14:15], v[14:15], 1.0 op_sel_hi:[1,0]
	v_pk_add_f32 v[12:13], v[12:13], 1.0 op_sel_hi:[1,0]
	v_pk_mul_f32 v[88:89], v[10:11], v[14:15]
	v_pk_mul_f32 v[90:91], v[8:9], v[12:13]
	v_lshl_add_u64 v[136:137], v[22:23], 0, v[124:125]
	global_load_dwordx4 v[8:11], v[136:137], off
	global_load_dwordx4 v[12:15], v119, s[2:3]
	s_nop 0
	v_lshl_add_u64 v[136:137], v[18:19], 0, v[126:127]
	global_load_dwordx4 v[18:21], v[136:137], off
	s_lshl_b64 s[2:3], s[0:1], 24
	s_add_u32 s16, s16, s2
	s_addc_u32 s17, s17, s3
	s_lshl_b64 s[2:3], s[0:1], 12
	s_add_u32 s2, s5, s2
	s_addc_u32 s3, s6, s3
	s_add_u32 s20, s2, 0x590000
	s_addc_u32 s61, s3, 0
	s_lshl_b64 s[2:3], s[0:1], 23
	s_add_u32 s2, s5, s2
	s_addc_u32 s3, s6, s3
	s_lshl_b32 s0, s0, 10
	s_ashr_i32 s1, s0, 31
	s_lshl_b64 s[0:1], s[0:1], 2
	s_add_u32 s0, s5, s0
	s_addc_u32 s1, s6, s1
	v_cndmask_b32_e32 v17, v221, v17, vcc
	v_cmp_lt_i32_e32 vcc, v218, v222
	v_lshlrev_b32_e32 v105, 2, v17
	s_sub_i32 s76, s7, s19
	v_cndmask_b32_e32 v17, v221, v218, vcc
	v_cmp_lt_i32_e32 vcc, v219, v222
	v_lshlrev_b32_e32 v106, 2, v17
	s_waitcnt vmcnt(0)
	v_pk_add_f32 v[20:21], v[20:21], 1.0 op_sel_hi:[1,0]
	v_pk_add_f32 v[18:19], v[18:19], 1.0 op_sel_hi:[1,0]
	v_pk_mul_f32 v[92:93], v[14:15], v[20:21]
	v_pk_mul_f32 v[94:95], v[12:13], v[18:19]
	v_lshl_add_u64 v[136:137], v[22:23], 0, v[126:127]
	global_load_dwordx4 v[12:15], v[136:137], off
	v_lshl_add_u64 v[18:19], s[0:1], 0, v[162:163]
	s_mov_b64 s[0:1], 0x598000
	v_lshlrev_b32_e32 v162, 3, v16
	v_lshl_add_u64 v[96:97], v[18:19], 0, s[0:1]
	v_lshl_add_u64 v[18:19], s[2:3], 0, v[162:163]
	s_mov_b64 s[0:1], 0x6e00000
	v_lshl_add_u64 v[98:99], v[18:19], 0, s[0:1]
	s_sub_i32 s0, s18, s63
	s_add_i32 s1, s0, 1
	v_cndmask_b32_e32 v17, v221, v219, vcc
	v_cmp_lt_i32_e32 vcc, v254, v222
	s_mul_i32 s1, s4, s1
	v_lshlrev_b32_e32 v107, 2, v17
	v_cndmask_b32_e32 v17, v221, v254, vcc
	v_cmp_lt_i32_e32 vcc, v223, v222
	s_add_i32 s18, s7, s1
	s_add_i32 s1, s0, 2
	s_add_i32 s0, s0, 3
	v_lshlrev_b32_e32 v108, 2, v17
	v_cndmask_b32_e32 v17, v221, v223, vcc
	s_lshl_b32 s63, s4, 2
	s_mul_i32 s1, s4, s1
	s_mul_i32 s4, s4, s0
	v_lshlrev_b32_e32 v109, 2, v17
	s_add_i32 s74, s7, s1
	s_add_i32 s75, s7, s4
	s_branch .LBB0_1142

; __device__ __forceinline__ unsigned pk2(float lo, float hi) { return f2bf(lo) | (f2bf(hi) << 16); }
; __device__ __forceinline__ void norm_mod_phase(const float* x, const float* x0src, size_t x0stride, float* h0buf, const float* g, const float* sh, const float* sc, bf16* XN, int gw, int NGW, int lane) {
;     ...
;     for (int k = 0; k < rpw; k += 4) {
;         f32x4 v[4][4];
; #pragma unroll
;         for (int r = 0; r < 4; ++r) { const int t = wi + wpb * (k + r); const bool t0 = t == 0;
;             const f32x4* xr = (const f32x4*)(t0 ? x0src + (size_t)b * x0stride : x + ((size_t)b * T + t) * D) + lane;
; #pragma unroll
;             for (int j = 0; j < 4; ++j) v[r][j] = xr[64 * j]; }
;         __builtin_amdgcn_sched_barrier(0);
; #pragma unroll
;         for (int r = 0; r < 4; ++r) { const int t = wi + wpb * (k + r); const bool t0 = t == 0; const size_t row = (size_t)b * T + t;
;             float ss = 0.f;
; #pragma unroll
;             for (int j = 0; j < 4; ++j) ss += (v[r][j].x * v[r][j].x + v[r][j].y * v[r][j].y) + (v[r][j].z * v[r][j].z + v[r][j].w * v[r][j].w);
;             const float rstd = 1.f / sqrtf(wave_sum(ss) * (1.f / D) + EPS);
; #pragma unroll
;             for (int j = 0; j < 4; ++j) { const int col = 4 * lane + 256 * j;
;                 const f32x4 h = v[r][j] * rstd * gm[j] + s0[j];
;                 v2u o; o.x = pk2(h.x, h.y); o.y = pk2(h.z, h.w);
;                 *(v2u*)(XN + row * D + col) = o;
.LBB0_1142:
	s_add_i32 s0, s9, s76
	s_ashr_i32 s1, s0, 31
	s_lshl_b64 s[2:3], s[0:1], 12
	s_add_u32 s4, s16, s2
	s_addc_u32 s5, s17, s3
	s_cmp_eq_u32 s0, 0
	s_cselect_b64 s[70:71], -1, 0
	s_and_b64 s[2:3], s[70:71], exec
	s_cselect_b32 s72, s20, s4
	s_cselect_b32 s73, s61, s5
	s_add_i32 s68, s9, s18
	s_ashr_i32 s69, s68, 31
	s_lshl_b64 s[2:3], s[68:69], 12
	s_add_u32 s4, s16, s2
	s_addc_u32 s5, s17, s3
	s_cmp_eq_u32 s68, 0
	s_cselect_b64 s[66:67], -1, 0
	s_and_b64 s[2:3], s[66:67], exec
	s_cselect_b32 s78, s20, s4
	s_cselect_b32 s79, s61, s5
	s_add_i32 s64, s9, s74
	s_ashr_i32 s65, s64, 31
	s_lshl_b64 s[2:3], s[64:65], 12
	s_add_u32 s4, s16, s2
	s_addc_u32 s5, s17, s3
	s_cmp_eq_u32 s64, 0
	s_cselect_b64 s[6:7], -1, 0
	s_and_b64 s[2:3], s[6:7], exec
	s_cselect_b32 s80, s20, s4
	s_cselect_b32 s81, s61, s5
	s_add_i32 s4, s9, s75
	s_ashr_i32 s5, s4, 31
	s_lshl_b64 s[2:3], s[4:5], 12
	s_add_u32 s19, s16, s2
	s_addc_u32 s34, s17, s3
	s_cmp_eq_u32 s4, 0
	s_cselect_b64 s[2:3], -1, 0
	s_and_b64 s[82:83], s[2:3], exec
	s_cselect_b32 s82, s20, s19
	s_cselect_b32 s83, s61, s34
	global_load_dwordx4 v[76:79], v116, s[72:73]
	global_load_dwordx4 v[72:75], v117, s[72:73]
	global_load_dwordx4 v[68:71], v118, s[72:73]
	global_load_dwordx4 v[64:67], v119, s[72:73]
	global_load_dwordx4 v[60:63], v116, s[78:79]
	global_load_dwordx4 v[56:59], v117, s[78:79]
	global_load_dwordx4 v[52:55], v118, s[78:79]
	global_load_dwordx4 v[48:51], v119, s[78:79]
	global_load_dwordx4 v[44:47], v116, s[80:81]
	global_load_dwordx4 v[40:43], v117, s[80:81]
	global_load_dwordx4 v[36:39], v118, s[80:81]
	global_load_dwordx4 v[32:35], v119, s[80:81]
	global_load_dwordx4 v[28:31], v116, s[82:83]
	global_load_dwordx4 v[24:27], v117, s[82:83]
	global_load_dwordx4 v[20:23], v118, s[82:83]
	global_load_dwordx4 v[16:19], v119, s[82:83]
	s_lshl_b64 s[72:73], s[0:1], 11
	s_cmp_lg_u32 s0, 0
	s_waitcnt vmcnt(15)
	v_pk_mul_f32 v[100:101], v[78:79], v[78:79]
	v_pk_mul_f32 v[102:103], v[76:77], v[76:77]
	s_waitcnt vmcnt(12)
	v_mul_f32_e32 v111, v64, v64
	v_pk_mov_b32 v[112:113], v[102:103], v[100:101] op_sel:[1,0]
	v_mov_b32_e32 v103, v101
	v_pk_add_f32 v[100:101], v[112:113], v[102:103]
	v_pk_mul_f32 v[102:103], v[74:75], v[74:75]
	v_pk_mul_f32 v[112:113], v[72:73], v[72:73]
	v_pk_add_f32 v[100:101], v[100:101], v[100:101] op_sel:[0,1] op_sel_hi:[1,0]
	v_pk_mov_b32 v[114:115], v[112:113], v[102:103] op_sel:[1,0]
	v_mov_b32_e32 v113, v103
	v_pk_add_f32 v[102:103], v[114:115], v[112:113]
	v_mul_f32_e32 v112, v65, v65
	v_pk_add_f32 v[102:103], v[102:103], v[102:103] op_sel:[0,1] op_sel_hi:[1,0]
	v_mov_b32_e32 v101, v111
	v_mov_b32_e32 v103, v112
	v_pk_add_f32 v[100:101], v[100:101], v[102:103]
	v_mul_f32_e32 v102, v69, v69
	v_mul_f32_e32 v113, v66, v66
	v_pk_fma_f32 v[102:103], v[68:69], v[68:69], v[102:103] op_sel_hi:[1,1,0]
	v_mul_f32_e32 v112, v71, v71
	v_mul_f32_e32 v114, v67, v67
	v_mov_b32_e32 v103, v113
	v_pk_fma_f32 v[112:113], v[70:71], v[70:71], v[112:113] op_sel_hi:[1,1,0]
	s_nop 0
	v_mov_b32_e32 v113, v114
	v_pk_add_f32 v[102:103], v[102:103], v[112:113]
	s_nop 0
	v_pk_add_f32 v[100:101], v[100:101], v[102:103]
	s_nop 0
	v_add_f32_e32 v100, v100, v101
	ds_bpermute_b32 v101, v104, v100
	s_waitcnt lgkmcnt(0)
	v_add_f32_e32 v100, v100, v101
	ds_bpermute_b32 v101, v105, v100
	s_waitcnt lgkmcnt(0)
	v_add_f32_e32 v100, v100, v101
	ds_bpermute_b32 v101, v106, v100
	s_waitcnt lgkmcnt(0)
	v_add_f32_e32 v100, v100, v101
	ds_bpermute_b32 v101, v107, v100
	s_waitcnt lgkmcnt(0)
	v_add_f32_e32 v100, v100, v101
	ds_bpermute_b32 v101, v108, v100
	s_waitcnt lgkmcnt(0)
	v_add_f32_e32 v100, v100, v101
	ds_bpermute_b32 v101, v109, v100
	s_waitcnt lgkmcnt(0)
	v_add_f32_e32 v100, v100, v101
	v_fmamk_f32 v100, v100, 0x3a800000, v161
	v_mul_f32_e32 v101, 0x4f800000, v100
	v_cmp_gt_f32_e32 vcc, s58, v100
	s_nop 1
	v_cndmask_b32_e32 v100, v100, v101, vcc
	v_sqrt_f32_e32 v101, v100
	s_nop 0
	v_add_u32_e32 v102, -1, v101
	v_add_u32_e32 v103, 1, v101
	v_fma_f32 v111, -v102, v101, v100
	v_fma_f32 v112, -v103, v101, v100
	v_cmp_ge_f32_e64 s[0:1], 0, v111
	s_nop 1
	v_cndmask_b32_e64 v101, v101, v102, s[0:1]
	v_cmp_lt_f32_e64 s[0:1], 0, v112
	s_nop 1
	v_cndmask_b32_e64 v101, v101, v103, s[0:1]
	v_mul_f32_e32 v102, 0x37800000, v101
	v_cndmask_b32_e32 v101, v101, v102, vcc
	v_cmp_class_f32_e32 vcc, v100, v177
	s_nop 1
	v_cndmask_b32_e32 v100, v101, v100, vcc
	v_div_scale_f32 v101, s[0:1], v100, v100, 1.0
	v_rcp_f32_e32 v102, v101
	v_div_scale_f32 v103, vcc, 1.0, v100, 1.0
	v_fma_f32 v111, -v101, v102, 1.0
	v_fmac_f32_e32 v102, v111, v102
	v_mul_f32_e32 v111, v103, v102
	v_fma_f32 v112, -v101, v111, v103
	v_fmac_f32_e32 v111, v112, v102
	v_fma_f32 v101, -v101, v111, v103
	v_div_fmas_f32 v101, v101, v102, v111
	v_div_fixup_f32 v100, v101, v100, 1.0
	v_pk_mul_f32 v[76:77], v[76:77], v[100:101] op_sel_hi:[1,0]
	v_pk_mul_f32 v[78:79], v[78:79], v[100:101] op_sel_hi:[1,0]
	v_pk_fma_f32 v[76:77], v[82:83], v[76:77], v[0:1]
	v_pk_fma_f32 v[78:79], v[80:81], v[78:79], v[2:3]
	v_bfe_u32 v101, v76, 16, 1
	v_add3_u32 v101, v76, v101, s59
	v_bfe_u32 v102, v77, 16, 1
	v_lshrrev_b32_e32 v101, 16, v101
	v_add3_u32 v102, v77, v102, s59
	v_and_or_b32 v112, v102, s60, v101
	v_bfe_u32 v101, v78, 16, 1
	v_add3_u32 v101, v78, v101, s59
	v_bfe_u32 v102, v79, 16, 1
	v_lshrrev_b32_e32 v101, 16, v101
	v_add3_u32 v102, v79, v102, s59
	v_and_or_b32 v113, v102, s60, v101
	v_lshl_add_u64 v[102:103], v[98:99], 0, s[72:73]
	v_mov_b64_e32 v[140:141], v[112:113]
	s_cbranch_scc1 .LBB0_1144
	v_lshl_add_u64 v[136:137], v[96:97], 0, v[120:121]
	global_store_dwordx4 v[136:137], v[76:79], off
.LBB0_1144:
	v_mov_b32_e32 v101, v100
	v_pk_mul_f32 v[72:73], v[72:73], v[100:101]
	v_mov_b32_e32 v76, v100
	v_pk_fma_f32 v[72:73], v[86:87], v[72:73], v[4:5]
	v_mov_b32_e32 v77, v100
	v_bfe_u32 v78, v72, 16, 1
	v_pk_mul_f32 v[74:75], v[74:75], v[76:77]
	v_add3_u32 v78, v72, v78, s59
	v_bfe_u32 v79, v73, 16, 1
	v_pk_fma_f32 v[74:75], v[84:85], v[74:75], v[6:7]
	v_lshrrev_b32_e32 v78, 16, v78
	v_add3_u32 v79, v73, v79, s59
	v_and_or_b32 v78, v79, s60, v78
	v_bfe_u32 v79, v74, 16, 1
	v_add3_u32 v79, v74, v79, s59
	v_bfe_u32 v111, v75, 16, 1
	v_lshrrev_b32_e32 v79, 16, v79
	v_add3_u32 v111, v75, v111, s59
	v_and_or_b32 v79, v111, s60, v79
	v_cndmask_b32_e64 v111, 0, 1, s[70:71]
	v_cmp_ne_u32_e64 s[0:1], 1, v111
	s_andn2_b64 vcc, exec, s[70:71]
	v_mov_b64_e32 v[142:143], v[78:79]
	v_lshl_add_u64 v[136:137], v[102:103], 0, v[128:129]
	global_store_dwordx4 v[136:137], v[140:143], off
	s_cbranch_vccnz .LBB0_1146
	v_lshl_add_u64 v[136:137], v[96:97], 0, v[122:123]
	global_store_dwordx4 v[136:137], v[72:75], off

; __device__ __forceinline__ unsigned pk2(float lo, float hi) { return f2bf(lo) | (f2bf(hi) << 16); }
; __device__ __forceinline__ void norm_mod_phase(const float* x, const float* x0src, size_t x0stride, float* h0buf, const float* g, const float* sh, const float* sc, bf16* XN, int gw, int NGW, int lane) {
;     ...
;         for (int r = 0; r < 4; ++r) { const int t = wi + wpb * (k + r); const bool t0 = t == 0; const size_t row = (size_t)b * T + t;
;             float ss = 0.f;
; #pragma unroll
;             for (int j = 0; j < 4; ++j) ss += (v[r][j].x * v[r][j].x + v[r][j].y * v[r][j].y) + (v[r][j].z * v[r][j].z + v[r][j].w * v[r][j].w);
;             const float rstd = 1.f / sqrtf(wave_sum(ss) * (1.f / D) + EPS);
; #pragma unroll
;             for (int j = 0; j < 4; ++j) { const int col = 4 * lane + 256 * j;
;                 const f32x4 h = v[r][j] * rstd * gm[j] + s0[j];
;                 v2u o; o.x = pk2(h.x, h.y); o.y = pk2(h.z, h.w);
;                 *(v2u*)(XN + row * D + col) = o;
;                 if (t0) *(f32x4*)(h0buf + b * D + col) = h; } }
.LBB0_1150:
	s_waitcnt vmcnt(13)
	s_nop 0
	v_pk_mul_f32 v[64:65], v[62:63], v[62:63]
	v_pk_mul_f32 v[66:67], v[60:61], v[60:61]
	s_nop 0
	v_pk_mov_b32 v[68:69], v[66:67], v[64:65] op_sel:[1,0]
	v_mov_b32_e32 v67, v65
	v_pk_add_f32 v[64:65], v[68:69], v[66:67]
	s_waitcnt vmcnt(12)
	v_pk_mul_f32 v[66:67], v[58:59], v[58:59]
	v_pk_mul_f32 v[68:69], v[56:57], v[56:57]
	v_pk_add_f32 v[64:65], v[64:65], v[64:65] op_sel:[0,1] op_sel_hi:[1,0]
	v_pk_mov_b32 v[70:71], v[68:69], v[66:67] op_sel:[1,0]
	v_mov_b32_e32 v69, v67
	v_pk_add_f32 v[66:67], v[70:71], v[68:69]
	s_waitcnt vmcnt(10)
	v_mul_f32_e32 v68, v48, v48
	v_mul_f32_e32 v69, v49, v49
	v_pk_add_f32 v[66:67], v[66:67], v[66:67] op_sel:[0,1] op_sel_hi:[1,0]
	v_mov_b32_e32 v65, v68
	v_mov_b32_e32 v67, v69
	v_pk_add_f32 v[64:65], v[64:65], v[66:67]
	v_mul_f32_e32 v66, v53, v53
	v_mul_f32_e32 v68, v55, v55
	v_mul_f32_e32 v70, v50, v50
	v_mul_f32_e32 v71, v51, v51
	v_pk_fma_f32 v[66:67], v[52:53], v[52:53], v[66:67] op_sel_hi:[1,1,0]
	v_pk_fma_f32 v[68:69], v[54:55], v[54:55], v[68:69] op_sel_hi:[1,1,0]
	v_mov_b32_e32 v67, v70
	v_mov_b32_e32 v69, v71
	v_pk_add_f32 v[66:67], v[66:67], v[68:69]
	s_nop 0
	v_pk_add_f32 v[64:65], v[64:65], v[66:67]
	s_nop 0
	v_add_f32_e32 v64, v64, v65
	ds_bpermute_b32 v65, v104, v64
	s_waitcnt lgkmcnt(0)
	v_add_f32_e32 v64, v64, v65
	ds_bpermute_b32 v65, v105, v64
	s_waitcnt lgkmcnt(0)
	v_add_f32_e32 v64, v64, v65
	ds_bpermute_b32 v65, v106, v64
	s_waitcnt lgkmcnt(0)
	v_add_f32_e32 v64, v64, v65
	ds_bpermute_b32 v65, v107, v64
	s_waitcnt lgkmcnt(0)
	v_add_f32_e32 v64, v64, v65
	ds_bpermute_b32 v65, v108, v64
	s_waitcnt lgkmcnt(0)
	v_add_f32_e32 v64, v64, v65
	ds_bpermute_b32 v65, v109, v64
	s_waitcnt lgkmcnt(0)
	v_add_f32_e32 v64, v64, v65
	v_fmamk_f32 v64, v64, 0x3a800000, v161
	v_mul_f32_e32 v65, 0x4f800000, v64
	v_cmp_gt_f32_e32 vcc, s58, v64
	s_nop 1
	v_cndmask_b32_e32 v64, v64, v65, vcc
	v_sqrt_f32_e32 v65, v64
	s_nop 0
	v_add_u32_e32 v66, -1, v65
	v_add_u32_e32 v67, 1, v65
	v_fma_f32 v68, -v66, v65, v64
	v_fma_f32 v69, -v67, v65, v64
	v_cmp_ge_f32_e64 s[0:1], 0, v68
	s_nop 1
	v_cndmask_b32_e64 v65, v65, v66, s[0:1]
	v_cmp_lt_f32_e64 s[0:1], 0, v69
	s_nop 1
	v_cndmask_b32_e64 v65, v65, v67, s[0:1]
	v_mul_f32_e32 v66, 0x37800000, v65
	v_cndmask_b32_e32 v65, v65, v66, vcc
	v_cmp_class_f32_e32 vcc, v64, v177
	s_nop 1
	v_cndmask_b32_e32 v64, v65, v64, vcc
	v_div_scale_f32 v65, s[0:1], v64, v64, 1.0
	v_rcp_f32_e32 v66, v65
	v_div_scale_f32 v67, vcc, 1.0, v64, 1.0
	s_lshl_b64 s[0:1], s[68:69], 11
	v_fma_f32 v68, -v65, v66, 1.0
	v_fmac_f32_e32 v66, v68, v66
	v_mul_f32_e32 v68, v67, v66
	v_fma_f32 v69, -v65, v68, v67
	v_fmac_f32_e32 v68, v69, v66
	v_fma_f32 v65, -v65, v68, v67
	v_div_fmas_f32 v65, v65, v66, v68
	v_div_fixup_f32 v64, v65, v64, 1.0
	v_pk_mul_f32 v[60:61], v[60:61], v[64:65] op_sel_hi:[1,0]
	v_pk_mul_f32 v[62:63], v[62:63], v[64:65] op_sel_hi:[1,0]
	v_pk_fma_f32 v[60:61], v[82:83], v[60:61], v[0:1]
	v_pk_fma_f32 v[62:63], v[80:81], v[62:63], v[2:3]
	v_bfe_u32 v65, v60, 16, 1
	v_add3_u32 v65, v60, v65, s59
	v_bfe_u32 v66, v61, 16, 1
	v_lshrrev_b32_e32 v65, 16, v65
	v_add3_u32 v66, v61, v66, s59
	v_and_or_b32 v68, v66, s60, v65
	v_bfe_u32 v65, v62, 16, 1
	v_add3_u32 v65, v62, v65, s59
	v_bfe_u32 v66, v63, 16, 1
	v_lshrrev_b32_e32 v65, 16, v65
	v_add3_u32 v66, v63, v66, s59
	v_and_or_b32 v69, v66, s60, v65
	v_cndmask_b32_e64 v65, 0, 1, s[66:67]
	v_lshl_add_u64 v[66:67], v[98:99], 0, s[0:1]
	v_cmp_ne_u32_e64 s[0:1], 1, v65
	s_andn2_b64 vcc, exec, s[66:67]
	v_mov_b64_e32 v[140:141], v[68:69]
	s_cbranch_vccnz .LBB0_1152
	v_lshl_add_u64 v[136:137], v[96:97], 0, v[120:121]
	global_store_dwordx4 v[136:137], v[60:63], off

; __device__ __forceinline__ unsigned pk2(float lo, float hi) { return f2bf(lo) | (f2bf(hi) << 16); }
; __device__ __forceinline__ void norm_mod_phase(const float* x, const float* x0src, size_t x0stride, float* h0buf, const float* g, const float* sh, const float* sc, bf16* XN, int gw, int NGW, int lane) {
;     ...
;         for (int r = 0; r < 4; ++r) { const int t = wi + wpb * (k + r); const bool t0 = t == 0; const size_t row = (size_t)b * T + t;
;             float ss = 0.f;
; #pragma unroll
;             for (int j = 0; j < 4; ++j) ss += (v[r][j].x * v[r][j].x + v[r][j].y * v[r][j].y) + (v[r][j].z * v[r][j].z + v[r][j].w * v[r][j].w);
;             const float rstd = 1.f / sqrtf(wave_sum(ss) * (1.f / D) + EPS);
; #pragma unroll
;             for (int j = 0; j < 4; ++j) { const int col = 4 * lane + 256 * j;
;                 const f32x4 h = v[r][j] * rstd * gm[j] + s0[j];
;                 v2u o; o.x = pk2(h.x, h.y); o.y = pk2(h.z, h.w);
;                 *(v2u*)(XN + row * D + col) = o;
;                 if (t0) *(f32x4*)(h0buf + b * D + col) = h; } }
.LBB0_1158:
	s_waitcnt vmcnt(11)
	s_nop 0
	v_pk_mul_f32 v[48:49], v[46:47], v[46:47]
	v_pk_mul_f32 v[50:51], v[44:45], v[44:45]
	s_nop 0
	v_pk_mov_b32 v[52:53], v[50:51], v[48:49] op_sel:[1,0]
	v_mov_b32_e32 v51, v49
	v_pk_add_f32 v[48:49], v[52:53], v[50:51]
	s_waitcnt vmcnt(10)
	v_pk_mul_f32 v[50:51], v[42:43], v[42:43]
	v_pk_mul_f32 v[52:53], v[40:41], v[40:41]
	v_pk_add_f32 v[48:49], v[48:49], v[48:49] op_sel:[0,1] op_sel_hi:[1,0]
	v_pk_mov_b32 v[54:55], v[52:53], v[50:51] op_sel:[1,0]
	v_mov_b32_e32 v53, v51
	v_pk_add_f32 v[50:51], v[54:55], v[52:53]
	s_waitcnt vmcnt(8)
	v_mul_f32_e32 v52, v32, v32
	v_mul_f32_e32 v53, v33, v33
	v_pk_add_f32 v[50:51], v[50:51], v[50:51] op_sel:[0,1] op_sel_hi:[1,0]
	v_mov_b32_e32 v49, v52
	v_mov_b32_e32 v51, v53
	v_pk_add_f32 v[48:49], v[48:49], v[50:51]
	v_mul_f32_e32 v50, v37, v37
	v_mul_f32_e32 v52, v39, v39
	v_mul_f32_e32 v54, v34, v34
	v_mul_f32_e32 v55, v35, v35
	v_pk_fma_f32 v[50:51], v[36:37], v[36:37], v[50:51] op_sel_hi:[1,1,0]
	v_pk_fma_f32 v[52:53], v[38:39], v[38:39], v[52:53] op_sel_hi:[1,1,0]
	v_mov_b32_e32 v51, v54
	v_mov_b32_e32 v53, v55
	v_pk_add_f32 v[50:51], v[50:51], v[52:53]
	s_nop 0
	v_pk_add_f32 v[48:49], v[48:49], v[50:51]
	s_nop 0
	v_add_f32_e32 v48, v48, v49
	ds_bpermute_b32 v49, v104, v48
	s_waitcnt lgkmcnt(0)
	v_add_f32_e32 v48, v48, v49
	ds_bpermute_b32 v49, v105, v48
	s_waitcnt lgkmcnt(0)
	v_add_f32_e32 v48, v48, v49
	ds_bpermute_b32 v49, v106, v48
	s_waitcnt lgkmcnt(0)
	v_add_f32_e32 v48, v48, v49
	ds_bpermute_b32 v49, v107, v48
	s_waitcnt lgkmcnt(0)
	v_add_f32_e32 v48, v48, v49
	ds_bpermute_b32 v49, v108, v48
	s_waitcnt lgkmcnt(0)
	v_add_f32_e32 v48, v48, v49
	ds_bpermute_b32 v49, v109, v48
	s_waitcnt lgkmcnt(0)
	v_add_f32_e32 v48, v48, v49
	v_fmamk_f32 v48, v48, 0x3a800000, v161
	v_mul_f32_e32 v49, 0x4f800000, v48
	v_cmp_gt_f32_e32 vcc, s58, v48
	s_nop 1
	v_cndmask_b32_e32 v48, v48, v49, vcc
	v_sqrt_f32_e32 v49, v48
	s_nop 0
	v_add_u32_e32 v50, -1, v49
	v_add_u32_e32 v51, 1, v49
	v_fma_f32 v52, -v50, v49, v48
	v_fma_f32 v53, -v51, v49, v48
	v_cmp_ge_f32_e64 s[0:1], 0, v52
	s_nop 1
	v_cndmask_b32_e64 v49, v49, v50, s[0:1]
	v_cmp_lt_f32_e64 s[0:1], 0, v53
	s_nop 1
	v_cndmask_b32_e64 v49, v49, v51, s[0:1]
	v_mul_f32_e32 v50, 0x37800000, v49
	v_cndmask_b32_e32 v49, v49, v50, vcc
	v_cmp_class_f32_e32 vcc, v48, v177
	s_nop 1
	v_cndmask_b32_e32 v48, v49, v48, vcc
	v_div_scale_f32 v49, s[0:1], v48, v48, 1.0
	v_rcp_f32_e32 v50, v49
	v_div_scale_f32 v51, vcc, 1.0, v48, 1.0
	s_lshl_b64 s[0:1], s[64:65], 11
	v_fma_f32 v52, -v49, v50, 1.0
	v_fmac_f32_e32 v50, v52, v50
	v_mul_f32_e32 v52, v51, v50
	v_fma_f32 v53, -v49, v52, v51
	v_fmac_f32_e32 v52, v53, v50
	v_fma_f32 v49, -v49, v52, v51
	v_div_fmas_f32 v49, v49, v50, v52
	v_div_fixup_f32 v48, v49, v48, 1.0
	v_pk_mul_f32 v[44:45], v[44:45], v[48:49] op_sel_hi:[1,0]
	v_pk_mul_f32 v[46:47], v[46:47], v[48:49] op_sel_hi:[1,0]
	v_pk_fma_f32 v[44:45], v[82:83], v[44:45], v[0:1]
	v_pk_fma_f32 v[46:47], v[80:81], v[46:47], v[2:3]
	v_bfe_u32 v49, v44, 16, 1
	v_add3_u32 v49, v44, v49, s59
	v_bfe_u32 v50, v45, 16, 1
	v_lshrrev_b32_e32 v49, 16, v49
	v_add3_u32 v50, v45, v50, s59
	v_and_or_b32 v52, v50, s60, v49
	v_bfe_u32 v49, v46, 16, 1
	v_add3_u32 v49, v46, v49, s59
	v_bfe_u32 v50, v47, 16, 1
	v_lshrrev_b32_e32 v49, 16, v49
	v_add3_u32 v50, v47, v50, s59
	v_and_or_b32 v53, v50, s60, v49
	v_cndmask_b32_e64 v49, 0, 1, s[6:7]
	v_lshl_add_u64 v[50:51], v[98:99], 0, s[0:1]
	v_cmp_ne_u32_e64 s[0:1], 1, v49
	s_andn2_b64 vcc, exec, s[6:7]
	v_mov_b64_e32 v[140:141], v[52:53]
	s_cbranch_vccnz .LBB0_1160
	v_lshl_add_u64 v[136:137], v[96:97], 0, v[120:121]
	global_store_dwordx4 v[136:137], v[44:47], off

; __device__ __forceinline__ unsigned pk2(float lo, float hi) { return f2bf(lo) | (f2bf(hi) << 16); }
; __device__ __forceinline__ void norm_mod_phase(const float* x, const float* x0src, size_t x0stride, float* h0buf, const float* g, const float* sh, const float* sc, bf16* XN, int gw, int NGW, int lane) {
;     ...
;         for (int r = 0; r < 4; ++r) { const int t = wi + wpb * (k + r); const bool t0 = t == 0; const size_t row = (size_t)b * T + t;
;             float ss = 0.f;
; #pragma unroll
;             for (int j = 0; j < 4; ++j) ss += (v[r][j].x * v[r][j].x + v[r][j].y * v[r][j].y) + (v[r][j].z * v[r][j].z + v[r][j].w * v[r][j].w);
;             const float rstd = 1.f / sqrtf(wave_sum(ss) * (1.f / D) + EPS);
; #pragma unroll
;             for (int j = 0; j < 4; ++j) { const int col = 4 * lane + 256 * j;
;                 const f32x4 h = v[r][j] * rstd * gm[j] + s0[j];
;                 v2u o; o.x = pk2(h.x, h.y); o.y = pk2(h.z, h.w);
;                 *(v2u*)(XN + row * D + col) = o;
;                 if (t0) *(f32x4*)(h0buf + b * D + col) = h; } }
.LBB0_1166:
	s_waitcnt vmcnt(9)
	s_nop 0
	v_pk_mul_f32 v[32:33], v[30:31], v[30:31]
	v_pk_mul_f32 v[34:35], v[28:29], v[28:29]
	s_nop 0
	v_pk_mov_b32 v[36:37], v[34:35], v[32:33] op_sel:[1,0]
	v_mov_b32_e32 v35, v33
	v_pk_add_f32 v[32:33], v[36:37], v[34:35]
	s_waitcnt vmcnt(8)
	v_pk_mul_f32 v[34:35], v[26:27], v[26:27]
	v_pk_mul_f32 v[36:37], v[24:25], v[24:25]
	v_pk_add_f32 v[32:33], v[32:33], v[32:33] op_sel:[0,1] op_sel_hi:[1,0]
	v_pk_mov_b32 v[38:39], v[36:37], v[34:35] op_sel:[1,0]
	v_mov_b32_e32 v37, v35
	v_pk_add_f32 v[34:35], v[38:39], v[36:37]
	s_waitcnt vmcnt(6)
	v_mul_f32_e32 v36, v16, v16
	v_mul_f32_e32 v37, v17, v17
	v_pk_add_f32 v[34:35], v[34:35], v[34:35] op_sel:[0,1] op_sel_hi:[1,0]
	v_mov_b32_e32 v33, v36
	v_mov_b32_e32 v35, v37
	v_pk_add_f32 v[32:33], v[32:33], v[34:35]
	v_mul_f32_e32 v34, v21, v21
	v_mul_f32_e32 v36, v23, v23
	v_mul_f32_e32 v38, v18, v18
	v_mul_f32_e32 v39, v19, v19
	v_pk_fma_f32 v[34:35], v[20:21], v[20:21], v[34:35] op_sel_hi:[1,1,0]
	v_pk_fma_f32 v[36:37], v[22:23], v[22:23], v[36:37] op_sel_hi:[1,1,0]
	v_mov_b32_e32 v35, v38
	v_mov_b32_e32 v37, v39
	v_pk_add_f32 v[34:35], v[34:35], v[36:37]
	s_nop 0
	v_pk_add_f32 v[32:33], v[32:33], v[34:35]
	s_nop 0
	v_add_f32_e32 v32, v32, v33
	ds_bpermute_b32 v33, v104, v32
	s_waitcnt lgkmcnt(0)
	v_add_f32_e32 v32, v32, v33
	ds_bpermute_b32 v33, v105, v32
	s_waitcnt lgkmcnt(0)
	v_add_f32_e32 v32, v32, v33
	ds_bpermute_b32 v33, v106, v32
	s_waitcnt lgkmcnt(0)
	v_add_f32_e32 v32, v32, v33
	ds_bpermute_b32 v33, v107, v32
	s_waitcnt lgkmcnt(0)
	v_add_f32_e32 v32, v32, v33
	ds_bpermute_b32 v33, v108, v32
	s_waitcnt lgkmcnt(0)
	v_add_f32_e32 v32, v32, v33
	ds_bpermute_b32 v33, v109, v32
	s_waitcnt lgkmcnt(0)
	v_add_f32_e32 v32, v32, v33
	v_fmamk_f32 v32, v32, 0x3a800000, v161
	v_mul_f32_e32 v33, 0x4f800000, v32
	v_cmp_gt_f32_e32 vcc, s58, v32
	s_nop 1
	v_cndmask_b32_e32 v32, v32, v33, vcc
	v_sqrt_f32_e32 v33, v32
	s_nop 0
	v_add_u32_e32 v34, -1, v33
	v_add_u32_e32 v35, 1, v33
	v_fma_f32 v36, -v34, v33, v32
	v_fma_f32 v37, -v35, v33, v32
	v_cmp_ge_f32_e64 s[0:1], 0, v36
	s_nop 1
	v_cndmask_b32_e64 v33, v33, v34, s[0:1]
	v_cmp_lt_f32_e64 s[0:1], 0, v37
	s_nop 1
	v_cndmask_b32_e64 v33, v33, v35, s[0:1]
	v_mul_f32_e32 v34, 0x37800000, v33
	v_cndmask_b32_e32 v33, v33, v34, vcc
	v_cmp_class_f32_e32 vcc, v32, v177
	s_nop 1
	v_cndmask_b32_e32 v32, v33, v32, vcc
	v_div_scale_f32 v33, s[0:1], v32, v32, 1.0
	v_rcp_f32_e32 v34, v33
	v_div_scale_f32 v35, vcc, 1.0, v32, 1.0
	s_lshl_b64 s[0:1], s[4:5], 11
	v_fma_f32 v36, -v33, v34, 1.0
	v_fmac_f32_e32 v34, v36, v34
	v_mul_f32_e32 v36, v35, v34
	v_fma_f32 v37, -v33, v36, v35
	v_fmac_f32_e32 v36, v37, v34
	v_fma_f32 v33, -v33, v36, v35
	v_div_fmas_f32 v33, v33, v34, v36
	v_div_fixup_f32 v32, v33, v32, 1.0
	v_pk_mul_f32 v[28:29], v[28:29], v[32:33] op_sel_hi:[1,0]
	v_pk_mul_f32 v[30:31], v[30:31], v[32:33] op_sel_hi:[1,0]
	v_pk_fma_f32 v[28:29], v[82:83], v[28:29], v[0:1]
	v_pk_fma_f32 v[30:31], v[80:81], v[30:31], v[2:3]
	v_bfe_u32 v33, v28, 16, 1
	v_add3_u32 v33, v28, v33, s59
	v_bfe_u32 v34, v29, 16, 1
	v_lshrrev_b32_e32 v33, 16, v33
	v_add3_u32 v34, v29, v34, s59
	v_and_or_b32 v36, v34, s60, v33
	v_bfe_u32 v33, v30, 16, 1
	v_add3_u32 v33, v30, v33, s59
	v_bfe_u32 v34, v31, 16, 1
	v_lshrrev_b32_e32 v33, 16, v33
	v_add3_u32 v34, v31, v34, s59
	v_and_or_b32 v37, v34, s60, v33
	v_cndmask_b32_e64 v33, 0, 1, s[2:3]
	v_lshl_add_u64 v[34:35], v[98:99], 0, s[0:1]
	v_cmp_ne_u32_e64 s[0:1], 1, v33
	s_andn2_b64 vcc, exec, s[2:3]
	v_mov_b64_e32 v[140:141], v[36:37]
	s_cbranch_vccnz .LBB0_1168
	v_lshl_add_u64 v[136:137], v[96:97], 0, v[120:121]
	global_store_dwordx4 v[136:137], v[28:31], off
